# v54 + attention output stores widened: v_permlane16_swap pairs, 4x dwordx2 -> 2x dwordx4 per q-tile (docs 7.3 store widening)
# baseline (speedup 1.0000x reference)
.LBB0_128:
	s_and_b64 vcc, exec, s[6:7]
	s_cbranch_vccz .LBB0_150
	s_add_u32 s76, s18, 0x200000
	s_addc_u32 s77, s19, 0
	s_add_u32 s26, s18, 0x17e00000
	s_addc_u32 s27, s19, 0
	s_add_u32 s0, s18, 0x23600000
	s_addc_u32 s1, s19, 0
	v_writelane_b32 v209, s0, 26
	s_nop 1
	v_writelane_b32 v209, s1, 27
	s_nop 0
	v_readlane_b32 s0, v209, 53
	s_cmp_gt_i32 s0, 0
	s_mov_b64 s[0:1], -1
	s_cbranch_scc0 .LBB0_160
	v_readlane_b32 s2, v209, 47
	v_readlane_b32 s3, v209, 48
	s_and_b64 vcc, exec, s[2:3]
	s_cbranch_vccz .LBB0_152
	v_readlane_b32 s0, v252, 20
	v_mov_b32_e32 v2, v234
	v_readlane_b32 s1, v252, 21
	s_andn2_b64 vcc, exec, s[0:1]
	v_readfirstlane_b32 s0, v2
	s_cbranch_vccnz .LBB0_151
	v_readlane_b32 s2, v209, 49
	s_load_dwordx2 s[6:7], s[30:31], 0x68
	s_load_dwordx2 s[4:5], s[30:31], 0x80
	v_readlane_b32 s3, v209, 50
	s_lshl_b32 s2, s2, 5
	s_ashr_i32 s3, s2, 31
	s_lshl_b64 s[2:3], s[2:3], 2
	s_waitcnt lgkmcnt(0)
	s_add_u32 s2, s6, s2
	s_addc_u32 s3, s7, s3
	s_ashr_i32 s10, s0, 6
	v_lshlrev_b32_e32 v1, 4, v2
	v_readlane_b32 s0, v209, 26
	v_and_b32_e32 v204, 0x70, v1
	v_readlane_b32 s1, v209, 27
	v_and_b32_e32 v1, 7, v2
	v_lshl_add_u32 v5, v1, 4, 0
	v_lshl_add_u64 v[128:129], s[0:1], 0, v[204:205]
	s_movk_i32 s0, 0x1070
	v_bfe_u32 v0, v2, 4, 2
	v_lshrrev_b32_e32 v3, 2, v2
	v_mad_u32_u24 v1, v1, s0, v5
	s_mul_i32 s0, s10, 0x300
	v_readlane_b32 s20, v254, 37
	v_cmp_lt_i32_e32 vcc, v243, v238
	v_and_b32_e32 v138, 15, v2
	v_and_b32_e32 v3, 24, v3
	v_lshrrev_b32_e32 v4, 5, v2
	s_add_i32 s0, s0, s20
	v_lshlrev_b32_e32 v6, 4, v0
	v_lshlrev_b32_e32 v204, 3, v0
	v_cndmask_b32_e32 v0, v237, v243, vcc
	v_cmp_lt_i32_e32 vcc, v244, v238
	v_and_or_b32 v3, v4, 4, v3
	v_lshl_add_u32 v4, v138, 2, s0
	v_lshlrev_b32_e32 v140, 2, v0
	v_cndmask_b32_e32 v0, v237, v244, vcc
	v_sub_u32_e32 v139, v4, v6
	v_add_u32_e32 v8, 0, v6
	v_lshlrev_b32_e32 v141, 2, v0
	v_add_u32_e32 v4, 0x200, v2
	v_add_u32_e32 v0, 0x400, v2
	v_add_u32_e32 v6, 0x600, v2
	v_ashrrev_i32_e32 v143, 3, v2
	s_movk_i32 s0, 0x7f
	v_ashrrev_i32_e32 v144, 3, v4
	v_ashrrev_i32_e32 v145, 3, v0
	v_ashrrev_i32_e32 v146, 3, v6
	v_cmp_lt_i32_e64 s[60:61], s0, v143
	v_cmp_lt_i32_e64 s[62:63], s0, v144
	v_cmp_lt_i32_e64 s[64:65], s0, v145
	v_cmp_lt_i32_e64 s[66:67], s0, v146
	s_mov_b32 s0, 0x7fffffe3
	v_and_or_b32 v6, v143, s0, v3
	v_lshlrev_b32_e32 v10, 1, v6
	v_and_or_b32 v6, v144, s0, v3
	v_lshlrev_b32_e32 v12, 1, v6
	v_and_or_b32 v6, v145, s0, v3
	v_and_or_b32 v3, v146, s0, v3
	s_mov_b32 s21, 0x2aaaaaab
	v_lshlrev_b32_e32 v16, 1, v3
	v_mul_hi_i32 v3, v2, s21
	v_lshlrev_b32_e32 v14, 1, v6
	v_lshrrev_b32_e32 v6, 31, v3
	v_ashrrev_i32_e32 v3, 5, v3
	v_add_u32_e32 v3, v3, v6
	s_movk_i32 s22, 0xff40
	v_mad_u64_u32 v[6:7], s[0:1], v3, s22, v[2:3]
	v_subrev_u32_e32 v7, 32, v6
	v_cmp_lt_u32_e32 vcc, 47, v6
	v_cvt_f32_u32_e32 v6, v7
	v_lshl_add_u32 v148, v2, 2, s20
	v_mul_hi_i32 v2, v4, s21
	s_movk_i32 s6, 0x80
	v_mul_f32_e32 v6, 0x3d800000, v6
	v_log_f32_e32 v6, v6
	v_lshl_add_u32 v150, v4, 2, s20
	s_movk_i32 s7, 0x90
	v_mul_lo_u32 v9, v143, s7
	v_mul_f32_e32 v6, 0x40aaaaab, v6
	v_cvt_i32_f32_e32 v6, v6
	v_mul_lo_u32 v11, v144, s7
	v_mul_lo_u32 v13, v145, s7
	v_mul_lo_u32 v15, v146, s7
	v_min_i32_e32 v6, 15, v6
	v_add_u32_e32 v6, 16, v6
	v_cndmask_b32_e32 v6, v7, v6, vcc
	v_lshl_add_u32 v147, v6, 5, v3
	v_lshrrev_b32_e32 v3, 31, v2
	v_ashrrev_i32_e32 v2, 5, v2
	v_add_u32_e32 v6, v2, v3
	v_mad_u64_u32 v[2:3], s[0:1], v6, s22, v[4:5]
	v_subrev_u32_e32 v3, 32, v2
	v_cmp_lt_u32_e32 vcc, 47, v2
	v_cvt_f32_u32_e32 v2, v3
	v_cmp_gt_u32_e64 s[70:71], s6, v3
	s_mov_b32 s11, 0
	v_mad_u32_u24 v142, v138, s80, v8
	v_mul_f32_e32 v2, 0x3d800000, v2
	v_log_f32_e32 v2, v2
	v_bfe_u32 v130, v234, 4, 1
	v_mul_u32_u24_e32 v130, 24, v130
	v_add_u32_e32 v130, v204, v130
	v_mov_b32_e32 v131, 0
	v_lshl_add_u64 v[130:131], s[82:83], 0, v[130:131]
	v_cmp_gt_u32_e64 s[8:9], s6, v7
	v_lshl_add_u32 v152, v0, 2, s20
	v_mul_f32_e32 v2, 0x40aaaaab, v2
	v_cvt_i32_f32_e32 v2, v2
	v_mad_u32_u24 v153, v138, s7, v8
	v_add_u32_e32 v154, v5, v9
	v_add_u32_e32 v155, v1, v10
	v_min_i32_e32 v2, 15, v2
	v_add_u32_e32 v2, 16, v2
	v_cndmask_b32_e32 v2, v3, v2, vcc
	v_lshl_add_u32 v149, v2, 5, v6
	v_mul_hi_i32 v2, v0, s21
	v_lshrrev_b32_e32 v3, 31, v2
	v_ashrrev_i32_e32 v2, 5, v2
	v_add_u32_e32 v4, v2, v3
	v_mad_u64_u32 v[2:3], s[0:1], v4, s22, v[0:1]
	v_subrev_u32_e32 v3, 32, v2
	v_cmp_lt_u32_e32 vcc, 47, v2
	v_cvt_f32_u32_e32 v2, v3
	v_cmp_gt_u32_e64 s[72:73], s6, v3
	v_add_u32_e32 v156, v5, v11
	v_add_u32_e32 v157, v1, v12
	v_mul_f32_e32 v2, 0x3d800000, v2
	v_log_f32_e32 v2, v2
	v_add_u32_e32 v158, v5, v13
	v_add_u32_e32 v159, v1, v14
	v_add_u32_e32 v160, v5, v15
	v_mul_f32_e32 v2, 0x40aaaaab, v2
	v_cvt_i32_f32_e32 v2, v2
	v_add_u32_e32 v161, v1, v16
	v_lshlrev_b32_e32 v204, 1, v204
	v_readlane_b32 s28, v254, 30
	v_min_i32_e32 v2, 15, v2
	v_add_u32_e32 v2, 16, v2
	v_cndmask_b32_e32 v2, v3, v2, vcc
	v_lshl_add_u32 v151, v2, 5, v4
	v_readlane_b32 s29, v254, 29
	s_branch .LBB0_134
.LBB0_133:
	s_or_b64 exec, exec, s[0:1]
	s_add_i32 s0, s6, s10
	s_ashr_i32 s1, s0, 31
	s_lshl_b64 s[6:7], s[0:1], 2
	s_add_u32 s6, s2, s6
	v_or_b32_e32 v132, s21, v138
	s_addc_u32 s7, s3, s7
	v_ashrrev_i32_e32 v133, 31, v132
	s_lshl_b32 s0, s0, 6
	v_lshlrev_b64 v[136:137], 12, v[132:133]
	s_ashr_i32 s1, s0, 31
	ds_write_b32 v152, v0
	v_lshl_add_u64 v[0:1], s[26:27], 0, v[136:137]
	s_lshl_b64 s[0:1], s[0:1], 1
	v_lshl_add_u64 v[0:1], v[0:1], 0, s[0:1]
	s_waitcnt lgkmcnt(0)
	s_barrier
	global_load_dword v162, v205, s[6:7]
	v_lshl_add_u64 v[8:9], v[0:1], 0, v[204:205]
	s_mov_b32 s6, 0x10000
	v_add_co_u32_e32 v0, vcc, s6, v8
	global_load_dwordx4 v[84:87], v[8:9], off
	global_load_dwordx4 v[88:91], v[8:9], off offset:64
	v_addc_co_u32_e32 v1, vcc, 0, v9, vcc
	global_load_dwordx4 v[92:95], v[0:1], off
	global_load_dwordx4 v[96:99], v[0:1], off offset:64
	s_mov_b32 s6, 0x20000
	v_add_co_u32_e32 v0, vcc, s6, v8
	s_mov_b32 s6, 0x30000
	s_nop 0
	v_addc_co_u32_e32 v1, vcc, 0, v9, vcc
	global_load_dwordx4 v[36:39], v[0:1], off
	global_load_dwordx4 v[32:35], v[0:1], off offset:64
	v_add_co_u32_e32 v0, vcc, s6, v8
	s_mov_b32 s6, 0x40000
	s_nop 0
	v_addc_co_u32_e32 v1, vcc, 0, v9, vcc
	global_load_dwordx4 v[40:43], v[0:1], off
	global_load_dwordx4 v[44:47], v[0:1], off offset:64
	v_add_co_u32_e32 v0, vcc, s6, v8
	s_mov_b32 s6, 0x50000
	s_nop 0
	v_addc_co_u32_e32 v1, vcc, 0, v9, vcc
	global_load_dwordx4 v[20:23], v[0:1], off
	global_load_dwordx4 v[16:19], v[0:1], off offset:64
	v_add_co_u32_e32 v0, vcc, s6, v8
	s_mov_b32 s6, 0x60000
	s_nop 0
	v_addc_co_u32_e32 v1, vcc, 0, v9, vcc
	global_load_dwordx4 v[24:27], v[0:1], off
	global_load_dwordx4 v[28:31], v[0:1], off offset:64
	v_add_co_u32_e32 v0, vcc, s6, v8
	s_mov_b32 s6, 0x70000
	s_nop 0
	v_addc_co_u32_e32 v1, vcc, 0, v9, vcc
	v_add_co_u32_e32 v12, vcc, s6, v8
	global_load_dwordx4 v[4:7], v[0:1], off
	s_nop 0
	global_load_dwordx4 v[0:3], v[0:1], off offset:64
	v_addc_co_u32_e32 v13, vcc, 0, v9, vcc
	global_load_dwordx4 v[8:11], v[12:13], off
	s_nop 0
	global_load_dwordx4 v[12:15], v[12:13], off offset:64
	ds_read_b128 v[48:51], v153
	ds_read_b128 v[52:55], v153 offset:64
	s_cmp_eq_u32 s20, 0
	s_cselect_b64 vcc, -1, 0
	s_mov_b32 s7, 0xf149f2ca
	s_mov_b32 s6, 0x3fb8aa3b
	v_lshl_add_u64 v[134:135], v[130:131], 0, s[0:1]
	s_add_i32 s20, s11, 1
	v_readlane_b32 s36, v252, 10
	v_readlane_b32 s37, v252, 11
	s_waitcnt vmcnt(15) lgkmcnt(1)
	v_mfma_f32_16x16x32_bf16 v[56:59], v[48:51], v[84:87], 0
	v_mul_f32_e32 v133, 0x3fb8aa3b, v162
	s_waitcnt vmcnt(13)
	v_mfma_f32_16x16x32_bf16 v[48:51], v[48:51], v[92:95], 0
	s_waitcnt lgkmcnt(0)
	v_mfma_f32_16x16x32_bf16 v[100:103], v[52:55], v[88:91], v[56:59]
	s_waitcnt vmcnt(12)
	v_mfma_f32_16x16x32_bf16 v[48:51], v[52:55], v[96:99], v[48:51]
	ds_read_b128 v[52:55], v153 offset:2304
	ds_read_b128 v[56:59], v153 offset:2368
	s_waitcnt lgkmcnt(1)
	v_mfma_f32_16x16x32_bf16 v[60:63], v[52:55], v[84:87], 0
	v_mfma_f32_16x16x32_bf16 v[52:55], v[52:55], v[92:95], 0
	s_waitcnt lgkmcnt(0)
	v_mfma_f32_16x16x32_bf16 v[104:107], v[56:59], v[88:91], v[60:63]
	v_mfma_f32_16x16x32_bf16 v[52:55], v[56:59], v[96:99], v[52:55]
	ds_read_b128 v[56:59], v153 offset:4608
	s_nop 2
	ds_read_b128 v[60:63], v153 offset:4672
	s_waitcnt lgkmcnt(1)
	v_mfma_f32_16x16x32_bf16 v[64:67], v[56:59], v[84:87], 0
	v_mfma_f32_16x16x32_bf16 v[56:59], v[56:59], v[92:95], 0
	s_waitcnt lgkmcnt(0)
	v_mfma_f32_16x16x32_bf16 v[108:111], v[60:63], v[88:91], v[64:67]
	v_mfma_f32_16x16x32_bf16 v[56:59], v[60:63], v[96:99], v[56:59]
	ds_read_b128 v[60:63], v153 offset:6912
	s_nop 2
	ds_read_b128 v[64:67], v153 offset:6976
	s_waitcnt lgkmcnt(1)
	v_mfma_f32_16x16x32_bf16 v[68:71], v[60:63], v[84:87], 0
	v_mfma_f32_16x16x32_bf16 v[60:63], v[60:63], v[92:95], 0
	s_waitcnt lgkmcnt(0)
	v_mfma_f32_16x16x32_bf16 v[112:115], v[64:67], v[88:91], v[68:71]
	v_mfma_f32_16x16x32_bf16 v[60:63], v[64:67], v[96:99], v[60:63]
	ds_read_b128 v[64:67], v153 offset:9216
	s_nop 2
	ds_read_b128 v[68:71], v153 offset:9280
	s_waitcnt lgkmcnt(1)
	v_mfma_f32_16x16x32_bf16 v[72:75], v[64:67], v[84:87], 0
	v_mfma_f32_16x16x32_bf16 v[64:67], v[64:67], v[92:95], 0
	s_waitcnt lgkmcnt(0)
	v_mfma_f32_16x16x32_bf16 v[116:119], v[68:71], v[88:91], v[72:75]
	v_mfma_f32_16x16x32_bf16 v[64:67], v[68:71], v[96:99], v[64:67]
	ds_read_b128 v[68:71], v153 offset:11520
	s_nop 2
	ds_read_b128 v[72:75], v153 offset:11584
	s_waitcnt lgkmcnt(1)
	v_mfma_f32_16x16x32_bf16 v[76:79], v[68:71], v[84:87], 0
	v_mfma_f32_16x16x32_bf16 v[68:71], v[68:71], v[92:95], 0
	s_waitcnt lgkmcnt(0)
	v_mfma_f32_16x16x32_bf16 v[120:123], v[72:75], v[88:91], v[76:79]
	v_mfma_f32_16x16x32_bf16 v[68:71], v[72:75], v[96:99], v[68:71]
	ds_read_b128 v[72:75], v153 offset:13824
	s_nop 2
	ds_read_b128 v[76:79], v153 offset:13888
	s_waitcnt lgkmcnt(1)
	v_mfma_f32_16x16x32_bf16 v[80:83], v[72:75], v[84:87], 0
	v_mfma_f32_16x16x32_bf16 v[72:75], v[72:75], v[92:95], 0
	s_waitcnt lgkmcnt(0)
	v_mfma_f32_16x16x32_bf16 v[124:127], v[76:79], v[88:91], v[80:83]
	v_mfma_f32_16x16x32_bf16 v[72:75], v[76:79], v[96:99], v[72:75]
	ds_read_b128 v[76:79], v153 offset:16128
	s_nop 2
	ds_read_b128 v[80:83], v153 offset:16192
	s_waitcnt lgkmcnt(1)
	v_mfma_f32_16x16x32_bf16 v[164:167], v[76:79], v[84:87], 0
	v_mfma_f32_16x16x32_bf16 v[76:79], v[76:79], v[92:95], 0
	s_waitcnt lgkmcnt(0)
	v_mfma_f32_16x16x32_bf16 v[164:167], v[80:83], v[88:91], v[164:167]
	v_mfma_f32_16x16x32_bf16 v[76:79], v[80:83], v[96:99], v[76:79]
	ds_read_b128 v[80:83], v153 offset:18432
	ds_read_b128 v[168:171], v153 offset:18496
	s_waitcnt lgkmcnt(1)
	v_mfma_f32_16x16x32_bf16 v[172:175], v[80:83], v[84:87], 0
	v_mfma_f32_16x16x32_bf16 v[80:83], v[80:83], v[92:95], 0
	s_waitcnt lgkmcnt(0)
	v_mfma_f32_16x16x32_bf16 v[210:213], v[168:171], v[88:91], v[172:175]
	v_mfma_f32_16x16x32_bf16 v[80:83], v[168:171], v[96:99], v[80:83]
	ds_read_b128 v[168:171], v153 offset:20736
	s_nop 2
	ds_read_b128 v[172:175], v153 offset:20800
	s_waitcnt lgkmcnt(1)
	v_mfma_f32_16x16x32_bf16 v[84:87], v[168:171], v[84:87], 0
	s_waitcnt lgkmcnt(0)
	v_mfma_f32_16x16x32_bf16 v[214:217], v[172:175], v[88:91], v[84:87]
	v_mfma_f32_16x16x32_bf16 v[84:87], v[168:171], v[92:95], 0
	v_mov_b32_e32 v92, 0xf149f2ca
	v_cndmask_b32_e32 v92, 0, v92, vcc
	v_mfma_f32_16x16x32_bf16 v[84:87], v[172:175], v[96:99], v[84:87]
	ds_read2_b32 v[94:95], v139 offset0:159 offset1:160
	ds_read2_b32 v[96:97], v139 offset0:157 offset1:158
	ds_read2_b32 v[98:99], v139 offset0:143 offset1:144
	ds_read2_b32 v[176:177], v139 offset0:141 offset1:142
	ds_read2_b32 v[178:179], v139 offset0:127 offset1:128
	ds_read2_b32 v[180:181], v139 offset0:125 offset1:126
	ds_read2_b32 v[182:183], v139 offset0:111 offset1:112
	ds_read2_b32 v[184:185], v139 offset0:109 offset1:110
	ds_read2_b32 v[186:187], v139 offset0:95 offset1:96
	ds_read2_b32 v[188:189], v139 offset0:93 offset1:94
	ds_read2_b32 v[190:191], v139 offset0:79 offset1:80
	ds_read2_b32 v[192:193], v139 offset0:77 offset1:78
	ds_read2_b32 v[194:195], v139 offset0:63 offset1:64
	ds_read2_b32 v[196:197], v139 offset0:61 offset1:62
	ds_read2_b32 v[90:91], v139 offset0:47 offset1:48
	ds_read2_b32 v[88:89], v139 offset0:45 offset1:46
	ds_read2_b32 v[198:199], v139 offset0:31 offset1:32
	ds_read2_b32 v[218:219], v139 offset0:29 offset1:30
	ds_read2_b32 v[220:221], v139 offset0:15 offset1:16
	ds_read2_b32 v[222:223], v139 offset0:13 offset1:14
	s_waitcnt lgkmcnt(14)
	v_add_f32_e32 v169, v92, v95
	v_add_f32_e32 v170, v92, v94
	v_add_f32_e32 v93, v100, v169
	v_add_f32_e32 v94, v101, v170
	v_add_f32_e32 v171, v92, v97
	v_add_f32_e32 v172, v92, v96
	v_max3_f32 v95, v93, s7, v94
	v_add_f32_e32 v97, v102, v171
	v_add_f32_e32 v96, v103, v172
	v_add_f32_e32 v173, v92, v99
	v_add_f32_e32 v174, v92, v98
	v_max3_f32 v95, v95, v97, v96
	v_add_f32_e32 v99, v104, v173
	v_add_f32_e32 v98, v105, v174
	v_add_f32_e32 v175, v92, v177
	v_add_f32_e32 v176, v92, v176
	v_max3_f32 v95, v95, v99, v98
	v_add_f32_e32 v100, v106, v175
	v_add_f32_e32 v101, v107, v176
	v_add_f32_e32 v177, v92, v179
	v_add_f32_e32 v178, v92, v178
	v_max3_f32 v95, v95, v100, v101
	v_add_f32_e32 v102, v108, v177
	v_add_f32_e32 v103, v109, v178
	v_add_f32_e32 v179, v92, v181
	v_add_f32_e32 v180, v92, v180
	v_max3_f32 v95, v95, v102, v103
	v_add_f32_e32 v104, v110, v179
	v_add_f32_e32 v105, v111, v180
	s_waitcnt lgkmcnt(13)
	v_add_f32_e32 v181, v92, v183
	v_add_f32_e32 v182, v92, v182
	v_max3_f32 v95, v95, v104, v105
	v_add_f32_e32 v106, v112, v181
	v_add_f32_e32 v107, v113, v182
	s_waitcnt lgkmcnt(12)
	v_add_f32_e32 v183, v92, v185
	v_add_f32_e32 v184, v92, v184
	v_max3_f32 v95, v95, v106, v107
	v_add_f32_e32 v108, v114, v183
	v_add_f32_e32 v109, v115, v184
	s_waitcnt lgkmcnt(11)
	v_add_f32_e32 v185, v92, v187
	v_add_f32_e32 v186, v92, v186
	v_max3_f32 v95, v95, v108, v109
	v_add_f32_e32 v110, v116, v185
	v_add_f32_e32 v111, v117, v186
	s_waitcnt lgkmcnt(10)
	v_add_f32_e32 v187, v92, v189
	v_add_f32_e32 v188, v92, v188
	v_max3_f32 v95, v95, v110, v111
	v_add_f32_e32 v112, v118, v187
	v_add_f32_e32 v113, v119, v188
	s_waitcnt lgkmcnt(9)
	v_add_f32_e32 v189, v92, v191
	v_add_f32_e32 v190, v92, v190
	v_max3_f32 v95, v95, v112, v113
	v_add_f32_e32 v114, v120, v189
	v_add_f32_e32 v115, v121, v190
	s_waitcnt lgkmcnt(8)
	v_add_f32_e32 v191, v92, v193
	v_add_f32_e32 v192, v92, v192
	v_max3_f32 v95, v95, v114, v115
	v_add_f32_e32 v116, v122, v191
	v_add_f32_e32 v117, v123, v192
	s_waitcnt lgkmcnt(7)
	v_add_f32_e32 v193, v92, v195
	v_add_f32_e32 v194, v92, v194
	s_waitcnt lgkmcnt(5)
	v_add_f32_e32 v118, v92, v91
	v_max3_f32 v95, v95, v116, v117
	v_add_f32_e32 v224, v124, v193
	v_add_f32_e32 v225, v125, v194
	v_add_f32_e32 v195, v92, v197
	v_add_f32_e32 v196, v92, v196
	v_add_f32_e32 v228, v164, v118
	v_add_f32_e32 v118, v92, v90
	v_max3_f32 v95, v95, v224, v225
	v_add_f32_e32 v226, v126, v195
	v_add_f32_e32 v227, v127, v196
	v_add_f32_e32 v229, v165, v118
	s_waitcnt lgkmcnt(4)
	v_add_f32_e32 v118, v92, v89
	v_max3_f32 v95, v95, v226, v227
	v_add_f32_e32 v230, v166, v118
	v_add_f32_e32 v118, v92, v88
	v_max3_f32 v95, v95, v228, v229
	v_add_f32_e32 v231, v167, v118
	s_waitcnt lgkmcnt(3)
	v_add_f32_e32 v197, 0, v199
	v_add_f32_e32 v198, 0, v198
	s_waitcnt lgkmcnt(1)
	v_add_f32_e32 v118, 0, v221
	v_max3_f32 v95, v95, v230, v231
	v_add_f32_e32 v232, v210, v197
	v_add_f32_e32 v211, v211, v198
	v_add_f32_e32 v199, 0, v219
	v_add_f32_e32 v210, 0, v218
	v_add_f32_e32 v214, v214, v118
	v_add_f32_e32 v118, 0, v220
	v_max3_f32 v95, v95, v232, v211
	v_add_f32_e32 v212, v212, v199
	v_add_f32_e32 v213, v213, v210
	v_add_f32_e32 v215, v215, v118
	s_waitcnt lgkmcnt(0)
	v_add_f32_e32 v118, 0, v223
	v_max3_f32 v95, v95, v212, v213
	v_add_f32_e32 v216, v216, v118
	v_add_f32_e32 v118, 0, v222
	v_max3_f32 v95, v95, v214, v215
	v_add_f32_e32 v217, v217, v118
	v_max3_f32 v95, v95, v216, v217
	ds_bpermute_b32 v118, v140, v95
	v_add_f32_e32 v52, v52, v169
	v_add_f32_e32 v53, v53, v170
	v_add_f32_e32 v54, v54, v171
	v_add_f32_e32 v55, v55, v172
	s_waitcnt lgkmcnt(0)
	v_max_f32_e32 v118, v118, v118
	v_max_f32_e32 v95, v95, v118
	ds_bpermute_b32 v118, v141, v95
	v_add_f32_e32 v56, v56, v173
	v_add_f32_e32 v57, v57, v174
	v_add_f32_e32 v58, v58, v175
	v_add_f32_e32 v59, v59, v176
	s_waitcnt lgkmcnt(0)
	v_max3_f32 v218, v95, v118, v133
	v_sub_f32_e32 v93, v93, v218
	v_exp_f32_e32 v126, v93
	v_sub_f32_e32 v94, v94, v218
	v_exp_f32_e32 v127, v94
	v_sub_f32_e32 v94, v97, v218
	v_exp_f32_e32 v163, v94
	v_sub_f32_e32 v94, v96, v218
	v_exp_f32_e32 v164, v94
	v_sub_f32_e32 v94, v99, v218
	v_add_f32_e32 v93, 0, v126
	v_exp_f32_e32 v165, v94
	v_sub_f32_e32 v94, v98, v218
	v_add_f32_e32 v93, v127, v93
	v_exp_f32_e32 v166, v94
	v_sub_f32_e32 v94, v100, v218
	v_add_f32_e32 v93, v163, v93
	v_exp_f32_e32 v167, v94
	v_sub_f32_e32 v94, v101, v218
	v_add_f32_e32 v93, v164, v93
	v_exp_f32_e32 v168, v94
	v_sub_f32_e32 v94, v102, v218
	v_add_f32_e32 v93, v165, v93
	v_exp_f32_e32 v118, v94
	v_sub_f32_e32 v94, v103, v218
	v_add_f32_e32 v93, v166, v93
	v_exp_f32_e32 v119, v94
	v_sub_f32_e32 v94, v104, v218
	v_add_f32_e32 v93, v167, v93
	v_exp_f32_e32 v120, v94
	v_sub_f32_e32 v94, v105, v218
	v_add_f32_e32 v93, v168, v93
	v_exp_f32_e32 v121, v94
	v_sub_f32_e32 v94, v106, v218
	v_add_f32_e32 v93, v118, v93
	v_exp_f32_e32 v122, v94
	v_sub_f32_e32 v94, v107, v218
	v_add_f32_e32 v93, v119, v93
	v_exp_f32_e32 v123, v94
	v_sub_f32_e32 v94, v108, v218
	v_add_f32_e32 v93, v120, v93
	v_exp_f32_e32 v124, v94
	v_sub_f32_e32 v94, v109, v218
	v_add_f32_e32 v93, v121, v93
	v_exp_f32_e32 v125, v94
	v_sub_f32_e32 v94, v110, v218
	v_add_f32_e32 v93, v122, v93
	v_exp_f32_e32 v110, v94
	v_sub_f32_e32 v94, v111, v218
	v_add_f32_e32 v93, v123, v93
	v_exp_f32_e32 v111, v94
	v_sub_f32_e32 v94, v112, v218
	v_add_f32_e32 v93, v124, v93
	v_exp_f32_e32 v112, v94
	v_sub_f32_e32 v94, v113, v218
	v_add_f32_e32 v93, v125, v93
	v_exp_f32_e32 v113, v94
	v_sub_f32_e32 v94, v114, v218
	v_add_f32_e32 v93, v110, v93
	v_exp_f32_e32 v114, v94
	v_sub_f32_e32 v94, v115, v218
	v_add_f32_e32 v93, v111, v93
	v_exp_f32_e32 v115, v94
	v_sub_f32_e32 v94, v116, v218
	v_add_f32_e32 v93, v112, v93
	v_exp_f32_e32 v116, v94
	v_sub_f32_e32 v94, v117, v218
	v_add_f32_e32 v93, v113, v93
	v_exp_f32_e32 v117, v94
	v_sub_f32_e32 v94, v224, v218
	v_add_f32_e32 v93, v114, v93
	v_exp_f32_e32 v102, v94
	v_sub_f32_e32 v94, v225, v218
	v_add_f32_e32 v93, v115, v93
	v_exp_f32_e32 v103, v94
	v_sub_f32_e32 v94, v226, v218
	v_add_f32_e32 v93, v116, v93
	v_exp_f32_e32 v104, v94
	v_sub_f32_e32 v94, v227, v218
	v_add_f32_e32 v93, v117, v93
	v_exp_f32_e32 v105, v94
	v_sub_f32_e32 v94, v228, v218
	v_add_f32_e32 v93, v102, v93
	v_exp_f32_e32 v106, v94
	v_sub_f32_e32 v94, v229, v218
	v_add_f32_e32 v93, v103, v93
	v_exp_f32_e32 v107, v94
	v_sub_f32_e32 v94, v230, v218
	v_add_f32_e32 v93, v104, v93
	v_exp_f32_e32 v108, v94
	v_sub_f32_e32 v94, v231, v218
	v_add_f32_e32 v93, v105, v93
	v_exp_f32_e32 v109, v94
	v_sub_f32_e32 v94, v232, v218
	v_add_f32_e32 v93, v106, v93
	v_exp_f32_e32 v94, v94
	v_sub_f32_e32 v95, v211, v218
	v_add_f32_e32 v93, v107, v93
	v_exp_f32_e32 v95, v95
	v_sub_f32_e32 v96, v212, v218
	v_add_f32_e32 v93, v108, v93
	v_exp_f32_e32 v96, v96
	v_sub_f32_e32 v97, v213, v218
	v_add_f32_e32 v93, v109, v93
	v_exp_f32_e32 v97, v97
	v_sub_f32_e32 v98, v214, v218
	v_add_f32_e32 v93, v94, v93
	v_exp_f32_e32 v98, v98
	v_sub_f32_e32 v99, v215, v218
	v_add_f32_e32 v93, v95, v93
	v_exp_f32_e32 v99, v99
	v_sub_f32_e32 v100, v216, v218
	v_add_f32_e32 v93, v96, v93
	v_exp_f32_e32 v100, v100
	v_sub_f32_e32 v101, v217, v218
	v_add_f32_e32 v93, v97, v93
	v_exp_f32_e32 v101, v101
	v_add_f32_e32 v93, v98, v93
	v_add_f32_e32 v93, v99, v93
	v_add_f32_e32 v93, v100, v93
	v_add_f32_e32 v93, v101, v93
	ds_bpermute_b32 v211, v140, v93
	v_add_f32_e32 v60, v60, v177
	v_add_f32_e32 v61, v61, v178
	v_add_f32_e32 v62, v62, v179
	v_add_f32_e32 v63, v63, v180
	s_waitcnt lgkmcnt(0)
	v_add_f32_e32 v93, v93, v211
	ds_bpermute_b32 v211, v141, v93
	v_add_f32_e32 v64, v64, v181
	v_add_f32_e32 v170, v65, v182
	v_add_f32_e32 v171, v67, v184
	v_add_f32_e32 v172, v68, v185
	s_waitcnt lgkmcnt(0)
	v_add_f32_e32 v93, v93, v211
	v_fma_f32 v211, v162, s6, -v218
	v_exp_f32_e32 v211, v211
	v_add_f32_e32 v173, v69, v186
	v_add_f32_e32 v174, v70, v187
	v_add_f32_e32 v175, v71, v188
	v_add_f32_e32 v93, v211, v93
	v_div_scale_f32 v211, s[0:1], v93, v93, 1.0
	v_rcp_f32_e32 v212, v211
	v_add_f32_e32 v176, v72, v189
	v_add_f32_e32 v177, v73, v190
	v_add_f32_e32 v178, v74, v191
	v_fma_f32 v213, -v211, v212, 1.0
	v_fmac_f32_e32 v212, v213, v212
	v_div_scale_f32 v213, vcc, 1.0, v93, 1.0
	v_mul_f32_e32 v214, v213, v212
	v_fma_f32 v215, -v211, v214, v213
	v_fmac_f32_e32 v214, v215, v212
	v_fma_f32 v211, -v211, v214, v213
	v_div_fmas_f32 v211, v211, v212, v214
	ds_read2_b32 v[212:213], v139 offset0:175 offset1:176
	ds_read2_b32 v[214:215], v139 offset0:173 offset1:174
	v_div_fixup_f32 v93, v211, v93, 1.0
	v_add_f32_e32 v179, v75, v192
	v_add_f32_e32 v180, v76, v193
	s_waitcnt lgkmcnt(1)
	v_add_f32_e32 v211, v92, v213
	v_add_f32_e32 v48, v48, v211
	v_add_f32_e32 v211, v92, v212
	s_waitcnt lgkmcnt(0)
	v_add_f32_e32 v212, v92, v215
	v_add_f32_e32 v49, v49, v211
	v_add_f32_e32 v50, v50, v212
	v_add_f32_e32 v212, v92, v214
	v_max3_f32 v211, v48, s7, v49
	v_add_f32_e32 v51, v51, v212
	v_max3_f32 v211, v211, v50, v51
	v_max3_f32 v169, v211, v52, v53
	v_max3_f32 v169, v169, v54, v55
	v_max3_f32 v169, v169, v56, v57
	v_max3_f32 v169, v169, v58, v59
	v_max3_f32 v169, v169, v60, v61
	v_max3_f32 v169, v169, v62, v63
	v_max3_f32 v65, v169, v64, v170
	v_add_f32_e32 v169, v66, v183
	v_max3_f32 v65, v65, v169, v171
	v_max3_f32 v65, v65, v172, v173
	v_max3_f32 v65, v65, v174, v175
	v_max3_f32 v65, v65, v176, v177
	v_add_f32_e32 v66, 0, v91
	v_max3_f32 v65, v65, v178, v179
	v_add_f32_e32 v181, v77, v194
	v_add_f32_e32 v91, v80, v66
	v_add_f32_e32 v66, 0, v90
	v_max3_f32 v65, v65, v180, v181
	v_add_f32_e32 v182, v78, v195
	v_add_f32_e32 v183, v79, v196
	v_add_f32_e32 v90, v81, v66
	v_add_f32_e32 v66, 0, v89
	v_max3_f32 v65, v65, v182, v183
	v_add_f32_e32 v89, v82, v66
	v_add_f32_e32 v66, 0, v88
	v_max3_f32 v65, v65, v91, v90
	v_add_f32_e32 v184, v83, v66
	v_max3_f32 v65, v65, v89, v184
	v_add_f32_e32 v185, v84, v197
	v_add_f32_e32 v186, v85, v198
	v_max3_f32 v65, v65, v185, v186
	v_add_f32_e32 v187, v86, v199
	v_add_f32_e32 v188, v87, v210
	v_max3_f32 v65, v65, v187, v188
	ds_bpermute_b32 v66, v140, v65
	s_waitcnt lgkmcnt(0)
	v_max_f32_e32 v66, v66, v66
	v_max_f32_e32 v65, v65, v66
	ds_bpermute_b32 v66, v141, v65
	s_waitcnt lgkmcnt(0)
	v_max3_f32 v189, v65, v66, v133
	v_sub_f32_e32 v48, v48, v189
	v_exp_f32_e32 v81, v48
	v_sub_f32_e32 v49, v49, v189
	v_exp_f32_e32 v82, v49
	v_sub_f32_e32 v49, v50, v189
	v_exp_f32_e32 v83, v49
	v_sub_f32_e32 v49, v51, v189
	v_exp_f32_e32 v84, v49
	v_sub_f32_e32 v49, v52, v189
	v_add_f32_e32 v48, 0, v81
	v_exp_f32_e32 v85, v49
	v_sub_f32_e32 v49, v53, v189
	v_add_f32_e32 v48, v82, v48
	v_exp_f32_e32 v86, v49
	v_sub_f32_e32 v49, v54, v189
	v_add_f32_e32 v48, v83, v48
	v_exp_f32_e32 v87, v49
	v_sub_f32_e32 v49, v55, v189
	v_add_f32_e32 v48, v84, v48
	v_exp_f32_e32 v88, v49
	v_sub_f32_e32 v49, v56, v189
	v_add_f32_e32 v48, v85, v48
	v_exp_f32_e32 v73, v49
	v_sub_f32_e32 v49, v57, v189
	v_add_f32_e32 v48, v86, v48
	v_exp_f32_e32 v74, v49
	v_sub_f32_e32 v49, v58, v189
	v_add_f32_e32 v48, v87, v48
	v_exp_f32_e32 v75, v49
	v_sub_f32_e32 v49, v59, v189
	v_add_f32_e32 v48, v88, v48
	v_exp_f32_e32 v76, v49
	v_sub_f32_e32 v49, v60, v189
	v_add_f32_e32 v48, v73, v48
	v_exp_f32_e32 v77, v49
	v_sub_f32_e32 v49, v61, v189
	v_add_f32_e32 v48, v74, v48
	v_exp_f32_e32 v78, v49
	v_sub_f32_e32 v49, v62, v189
	v_add_f32_e32 v48, v75, v48
	v_exp_f32_e32 v79, v49
	v_sub_f32_e32 v49, v63, v189
	v_add_f32_e32 v48, v76, v48
	v_exp_f32_e32 v80, v49
	v_sub_f32_e32 v49, v64, v189
	v_add_f32_e32 v48, v77, v48
	v_exp_f32_e32 v65, v49
	v_sub_f32_e32 v49, v170, v189
	v_add_f32_e32 v48, v78, v48
	v_exp_f32_e32 v66, v49
	v_sub_f32_e32 v49, v169, v189
	v_add_f32_e32 v48, v79, v48
	v_exp_f32_e32 v67, v49
	v_sub_f32_e32 v49, v171, v189
	v_add_f32_e32 v48, v80, v48
	v_exp_f32_e32 v68, v49
	v_sub_f32_e32 v49, v172, v189
	v_add_f32_e32 v48, v65, v48
	v_exp_f32_e32 v69, v49
	v_sub_f32_e32 v49, v173, v189
	v_add_f32_e32 v48, v66, v48
	v_exp_f32_e32 v70, v49
	v_sub_f32_e32 v49, v174, v189
	v_add_f32_e32 v48, v67, v48
	v_exp_f32_e32 v71, v49
	v_sub_f32_e32 v49, v175, v189
	v_add_f32_e32 v48, v68, v48
	v_exp_f32_e32 v72, v49
	v_sub_f32_e32 v49, v176, v189
	v_add_f32_e32 v48, v69, v48
	v_exp_f32_e32 v57, v49
	v_sub_f32_e32 v49, v177, v189
	v_add_f32_e32 v48, v70, v48
	v_exp_f32_e32 v58, v49
	v_sub_f32_e32 v49, v178, v189
	v_add_f32_e32 v48, v71, v48
	v_exp_f32_e32 v59, v49
	v_sub_f32_e32 v49, v179, v189
	v_add_f32_e32 v48, v72, v48
	v_exp_f32_e32 v60, v49
	v_sub_f32_e32 v49, v180, v189
	v_add_f32_e32 v48, v57, v48
	v_exp_f32_e32 v61, v49
	v_sub_f32_e32 v49, v181, v189
	v_add_f32_e32 v48, v58, v48
	v_exp_f32_e32 v62, v49
	v_sub_f32_e32 v49, v182, v189
	v_add_f32_e32 v48, v59, v48
	v_exp_f32_e32 v63, v49
	v_sub_f32_e32 v49, v183, v189
	v_add_f32_e32 v48, v60, v48
	v_exp_f32_e32 v64, v49
	v_sub_f32_e32 v49, v91, v189
	v_add_f32_e32 v48, v61, v48
	v_exp_f32_e32 v49, v49
	v_sub_f32_e32 v50, v90, v189
	v_add_f32_e32 v48, v62, v48
	v_exp_f32_e32 v50, v50
	v_sub_f32_e32 v51, v89, v189
	v_add_f32_e32 v48, v63, v48
	v_exp_f32_e32 v51, v51
	v_sub_f32_e32 v52, v184, v189
	v_add_f32_e32 v48, v64, v48
	v_exp_f32_e32 v52, v52
	v_sub_f32_e32 v53, v185, v189
	v_add_f32_e32 v48, v49, v48
	v_exp_f32_e32 v53, v53
	v_sub_f32_e32 v54, v186, v189
	v_add_f32_e32 v48, v50, v48
	v_exp_f32_e32 v54, v54
	v_sub_f32_e32 v55, v187, v189
	v_add_f32_e32 v48, v51, v48
	v_exp_f32_e32 v55, v55
	v_sub_f32_e32 v56, v188, v189
	v_add_f32_e32 v48, v52, v48
	v_exp_f32_e32 v56, v56
	v_add_f32_e32 v48, v53, v48
	v_add_f32_e32 v48, v54, v48
	v_add_f32_e32 v48, v55, v48
	v_add_f32_e32 v48, v56, v48
	ds_bpermute_b32 v89, v140, v48
	s_waitcnt lgkmcnt(0)
	v_add_f32_e32 v48, v48, v89
	ds_bpermute_b32 v89, v141, v48
	s_waitcnt lgkmcnt(0)
	v_add_f32_e32 v48, v48, v89
	v_fma_f32 v89, v162, s6, -v189
	v_exp_f32_e32 v89, v89
	s_nop 0
	v_add_f32_e32 v48, v89, v48
	v_div_scale_f32 v89, s[0:1], v48, v48, 1.0
	v_rcp_f32_e32 v90, v89
	s_nop 0
	v_fma_f32 v91, -v89, v90, 1.0
	v_fmac_f32_e32 v90, v91, v90
	v_div_scale_f32 v91, vcc, 1.0, v48, 1.0
	v_mul_f32_e32 v169, v91, v90
	v_fma_f32 v170, -v89, v169, v91
	v_fmac_f32_e32 v169, v170, v90
	v_fma_f32 v89, -v89, v169, v91
	v_div_fmas_f32 v89, v89, v90, v169
	v_div_fixup_f32 v48, v89, v48, 1.0
	v_cvt_pk_bf16_f32 v170, v126, v127
	v_cvt_pk_bf16_f32 v171, v163, v164
	v_cvt_pk_bf16_f32 v172, v165, v166
	v_cvt_pk_bf16_f32 v173, v167, v168
	v_cvt_pk_bf16_f32 v82, v81, v82
	v_cvt_pk_bf16_f32 v83, v83, v84
	v_cvt_pk_bf16_f32 v84, v85, v86
	v_cvt_pk_bf16_f32 v85, v87, v88
	ds_read_b128 v[86:89], v142 offset:36864
	ds_read_b128 v[174:177], v142 offset:45312
	ds_read_b128 v[182:185], v142 offset:53760
	ds_read_b128 v[190:193], v142 offset:62208
	v_cvt_pk_bf16_f32 v118, v118, v119
	v_cvt_pk_bf16_f32 v119, v120, v121
	v_cvt_pk_bf16_f32 v120, v122, v123
	v_cvt_pk_bf16_f32 v121, v124, v125
	v_cvt_pk_bf16_f32 v74, v73, v74
	v_cvt_pk_bf16_f32 v75, v75, v76
	v_cvt_pk_bf16_f32 v76, v77, v78
	v_cvt_pk_bf16_f32 v77, v79, v80
	ds_read_b128 v[78:81], v142 offset:36928
	s_waitcnt lgkmcnt(4)
	v_mfma_f32_16x16x32_bf16 v[164:167], v[86:89], v[170:173], 0
	v_mfma_f32_16x16x32_bf16 v[86:89], v[86:89], v[82:85], 0
	s_waitcnt lgkmcnt(0)
	v_mfma_f32_16x16x32_bf16 v[122:125], v[78:81], v[118:121], v[164:167]
	v_mfma_f32_16x16x32_bf16 v[78:81], v[78:81], v[74:77], v[86:89]
	s_nop 4
	ds_read_b128 v[86:89], v142 offset:45376
	v_mfma_f32_16x16x32_bf16 v[178:181], v[174:177], v[170:173], 0
	v_mfma_f32_16x16x32_bf16 v[174:177], v[174:177], v[82:85], 0
	v_mfma_f32_16x16x32_bf16 v[186:189], v[182:185], v[170:173], 0
	v_mfma_f32_16x16x32_bf16 v[168:171], v[190:193], v[170:173], 0
	s_waitcnt lgkmcnt(0)
	v_mfma_f32_16x16x32_bf16 v[164:167], v[86:89], v[118:121], v[178:181]
	v_mfma_f32_16x16x32_bf16 v[86:89], v[86:89], v[74:77], v[174:177]
	s_nop 2
	ds_read_b128 v[172:175], v142 offset:53824
	v_mfma_f32_16x16x32_bf16 v[182:185], v[182:185], v[82:85], 0
	s_waitcnt lgkmcnt(0)
	v_mfma_f32_16x16x32_bf16 v[176:179], v[172:175], v[118:121], v[186:189]
	v_mfma_f32_16x16x32_bf16 v[172:175], v[172:175], v[74:77], v[182:185]
	s_nop 4
	ds_read_b128 v[180:183], v142 offset:62272
	v_mfma_f32_16x16x32_bf16 v[82:85], v[190:193], v[82:85], 0
	s_waitcnt lgkmcnt(0)
	v_mfma_f32_16x16x32_bf16 v[74:77], v[180:183], v[74:77], v[82:85]
	v_cvt_pk_bf16_f32 v82, v110, v111
	v_cvt_pk_bf16_f32 v83, v112, v113
	v_cvt_pk_bf16_f32 v84, v114, v115
	v_cvt_pk_bf16_f32 v85, v116, v117
	v_cvt_pk_bf16_f32 v66, v65, v66
	v_cvt_pk_bf16_f32 v67, v67, v68
	v_cvt_pk_bf16_f32 v68, v69, v70
	v_cvt_pk_bf16_f32 v69, v71, v72
	ds_read_b128 v[70:73], v142 offset:36992
	s_waitcnt lgkmcnt(0)
	s_nop 3
	v_mfma_f32_16x16x32_bf16 v[110:113], v[70:73], v[82:85], v[122:125]
	v_mfma_f32_16x16x32_bf16 v[70:73], v[70:73], v[66:69], v[78:81]
	s_nop 2
	ds_read_b128 v[78:81], v142 offset:45440
	s_waitcnt lgkmcnt(0)
	v_mfma_f32_16x16x32_bf16 v[114:117], v[78:81], v[82:85], v[164:167]
	s_nop 2
	ds_read_b128 v[164:167], v142 offset:62336
	v_mfma_f32_16x16x32_bf16 v[78:81], v[78:81], v[66:69], v[86:89]
	s_nop 2
	ds_read_b128 v[86:89], v142 offset:53888
	s_waitcnt lgkmcnt(0)
	v_mfma_f32_16x16x32_bf16 v[122:125], v[86:89], v[82:85], v[176:179]
	v_mfma_f32_16x16x32_bf16 v[86:89], v[86:89], v[66:69], v[172:175]
	v_mfma_f32_16x16x32_bf16 v[66:69], v[164:167], v[66:69], v[74:77]
	v_cvt_pk_bf16_f32 v74, v102, v103
	v_cvt_pk_bf16_f32 v75, v104, v105
	v_cvt_pk_bf16_f32 v76, v106, v107
	v_cvt_pk_bf16_f32 v77, v108, v109
	v_cvt_pk_bf16_f32 v58, v57, v58
	v_cvt_pk_bf16_f32 v59, v59, v60
	v_cvt_pk_bf16_f32 v60, v61, v62
	v_cvt_pk_bf16_f32 v61, v63, v64
	ds_read_b128 v[62:65], v142 offset:37056
	s_waitcnt lgkmcnt(0)
	v_mfma_f32_16x16x32_bf16 v[102:105], v[62:65], v[74:77], v[110:113]
	v_mfma_f32_16x16x32_bf16 v[62:65], v[62:65], v[58:61], v[70:73]
	s_nop 2
	ds_read_b128 v[70:73], v142 offset:45504
	s_waitcnt lgkmcnt(0)
	v_mfma_f32_16x16x32_bf16 v[106:109], v[70:73], v[74:77], v[114:117]
	v_mfma_f32_16x16x32_bf16 v[70:73], v[70:73], v[58:61], v[78:81]
	s_nop 2
	ds_read_b128 v[78:81], v142 offset:53952
	s_waitcnt lgkmcnt(0)
	v_mfma_f32_16x16x32_bf16 v[110:113], v[78:81], v[74:77], v[122:125]
	v_mfma_f32_16x16x32_bf16 v[78:81], v[78:81], v[58:61], v[86:89]
	s_nop 2
	ds_read_b128 v[86:89], v142 offset:62400
	s_waitcnt lgkmcnt(0)
	v_mfma_f32_16x16x32_bf16 v[58:61], v[86:89], v[58:61], v[66:69]
	v_cvt_pk_bf16_f32 v66, v94, v95
	v_cvt_pk_bf16_f32 v67, v96, v97
	v_cvt_pk_bf16_f32 v68, v98, v99
	v_cvt_pk_bf16_f32 v69, v100, v101
	v_cvt_pk_bf16_f32 v50, v49, v50
	v_cvt_pk_bf16_f32 v51, v51, v52
	v_cvt_pk_bf16_f32 v52, v53, v54
	v_cvt_pk_bf16_f32 v53, v55, v56
	ds_read_b128 v[54:57], v142 offset:37120
	v_mfma_f32_16x16x32_bf16 v[118:121], v[180:183], v[118:121], v[168:171]
	v_mfma_f32_16x16x32_bf16 v[82:85], v[164:167], v[82:85], v[118:121]
	v_mfma_f32_16x16x32_bf16 v[74:77], v[86:89], v[74:77], v[82:85]
	s_waitcnt lgkmcnt(0)
	v_mfma_f32_16x16x32_bf16 v[82:85], v[54:57], v[66:69], v[102:105]
	v_mfma_f32_16x16x32_bf16 v[54:57], v[54:57], v[50:53], v[62:65]
	s_nop 2
	ds_read_b128 v[62:65], v142 offset:45568
	s_waitcnt lgkmcnt(0)
	v_mfma_f32_16x16x32_bf16 v[86:89], v[62:65], v[66:69], v[106:109]
	s_nop 0
	v_mfma_f32_16x16x32_bf16 v[62:65], v[62:65], v[50:53], v[70:73]
	s_nop 2
	ds_read_b128 v[70:73], v142 offset:54016
	s_waitcnt lgkmcnt(0)
	v_mfma_f32_16x16x32_bf16 v[94:97], v[70:73], v[66:69], v[110:113]
	v_mfma_f32_16x16x32_bf16 v[70:73], v[70:73], v[50:53], v[78:81]
	s_nop 2
	ds_read_b128 v[78:81], v142 offset:62464
	s_waitcnt lgkmcnt(0)
	v_mfma_f32_16x16x32_bf16 v[50:53], v[78:81], v[50:53], v[58:61]
	s_nop 2
	v_lshl_add_u64 v[58:59], v[134:135], 0, v[136:137]
	v_mfma_f32_16x16x32_bf16 v[66:69], v[78:81], v[66:69], v[74:77]
	v_mul_f32_e32 v82, v93, v82
	v_mul_f32_e32 v83, v93, v83
	v_mul_f32_e32 v84, v93, v84
	v_mul_f32_e32 v85, v93, v85
	v_mul_f32_e32 v86, v93, v86
	v_mul_f32_e32 v87, v93, v87
	v_mul_f32_e32 v88, v93, v88
	v_mul_f32_e32 v89, v93, v89
	v_mul_f32_e32 v94, v93, v94
	v_mul_f32_e32 v95, v93, v95
	v_mul_f32_e32 v96, v93, v96
	v_mul_f32_e32 v97, v93, v97
	v_mul_f32_e32 v66, v93, v66
	v_mul_f32_e32 v67, v93, v67
	v_mul_f32_e32 v68, v93, v68
	v_mul_f32_e32 v69, v93, v69
	v_cvt_pk_bf16_f32 v82, v82, v83
	v_cvt_pk_bf16_f32 v83, v84, v85
	v_cvt_pk_bf16_f32 v84, v86, v87
	v_cvt_pk_bf16_f32 v85, v88, v89
	v_cvt_pk_bf16_f32 v94, v94, v95
	v_cvt_pk_bf16_f32 v95, v96, v97
	v_cvt_pk_bf16_f32 v96, v66, v67
	v_cvt_pk_bf16_f32 v97, v68, v69
	s_nop 1
	v_permlane16_swap_b32_e32 v82, v84
	v_permlane16_swap_b32_e32 v83, v85
	v_permlane16_swap_b32_e32 v94, v96
	v_permlane16_swap_b32_e32 v95, v97
	global_store_dwordx4 v[58:59], v[82:85], off
	global_store_dwordx4 v[58:59], v[94:97], off offset:64
	v_or_b32_e32 v58, 16, v132
	v_ashrrev_i32_e32 v59, 31, v58
	v_lshlrev_b64 v[58:59], 12, v[58:59]
	v_lshl_add_u64 v[58:59], v[134:135], 0, v[58:59]
	v_mul_f32_e32 v54, v48, v54
	v_mul_f32_e32 v55, v48, v55
	v_mul_f32_e32 v56, v48, v56
	v_mul_f32_e32 v57, v48, v57
	v_mul_f32_e32 v62, v48, v62
	v_mul_f32_e32 v63, v48, v63
	v_mul_f32_e32 v64, v48, v64
	v_mul_f32_e32 v65, v48, v65
	v_mul_f32_e32 v70, v48, v70
	v_mul_f32_e32 v71, v48, v71
	v_mul_f32_e32 v72, v48, v72
	v_mul_f32_e32 v73, v48, v73
	v_mul_f32_e32 v50, v48, v50
	v_mul_f32_e32 v51, v48, v51
	v_mul_f32_e32 v52, v48, v52
	v_mul_f32_e32 v53, v48, v53
	v_cvt_pk_bf16_f32 v54, v54, v55
	v_cvt_pk_bf16_f32 v55, v56, v57
	v_cvt_pk_bf16_f32 v56, v62, v63
	v_cvt_pk_bf16_f32 v57, v64, v65
	v_cvt_pk_bf16_f32 v70, v70, v71
	v_cvt_pk_bf16_f32 v71, v72, v73
	v_cvt_pk_bf16_f32 v72, v50, v51
	v_cvt_pk_bf16_f32 v73, v52, v53
	s_nop 1
	v_permlane16_swap_b32_e32 v54, v56
	v_permlane16_swap_b32_e32 v55, v57
	v_permlane16_swap_b32_e32 v70, v72
	v_permlane16_swap_b32_e32 v71, v73
	global_store_dwordx4 v[58:59], v[54:57], off
	global_store_dwordx4 v[58:59], v[70:73], off offset:64
	ds_read_b128 v[48:51], v153 offset:4608
	ds_read_b128 v[52:55], v153 offset:4672
	s_waitcnt vmcnt(15) lgkmcnt(1)
	v_mfma_f32_16x16x32_bf16 v[56:59], v[48:51], v[36:39], 0
	s_waitcnt vmcnt(13)
	v_mfma_f32_16x16x32_bf16 v[48:51], v[48:51], v[40:43], 0
	s_waitcnt lgkmcnt(0)
	v_mfma_f32_16x16x32_bf16 v[84:87], v[52:55], v[32:35], v[56:59]
	s_waitcnt vmcnt(12)
	v_mfma_f32_16x16x32_bf16 v[48:51], v[52:55], v[44:47], v[48:51]
	ds_read_b128 v[52:55], v153 offset:6912
	s_nop 0
	ds_read_b128 v[56:59], v153 offset:6976
	s_waitcnt lgkmcnt(1)
	v_mfma_f32_16x16x32_bf16 v[60:63], v[52:55], v[36:39], 0
	v_mfma_f32_16x16x32_bf16 v[52:55], v[52:55], v[40:43], 0
	s_waitcnt lgkmcnt(0)
	v_mfma_f32_16x16x32_bf16 v[88:91], v[56:59], v[32:35], v[60:63]
	v_mfma_f32_16x16x32_bf16 v[52:55], v[56:59], v[44:47], v[52:55]
	ds_read_b128 v[56:59], v153 offset:9216
	s_nop 2
	ds_read_b128 v[60:63], v153 offset:9280
	s_waitcnt lgkmcnt(1)
	v_mfma_f32_16x16x32_bf16 v[64:67], v[56:59], v[36:39], 0
	v_mfma_f32_16x16x32_bf16 v[56:59], v[56:59], v[40:43], 0
	s_waitcnt lgkmcnt(0)
	v_mfma_f32_16x16x32_bf16 v[94:97], v[60:63], v[32:35], v[64:67]
	v_mfma_f32_16x16x32_bf16 v[56:59], v[60:63], v[44:47], v[56:59]
	ds_read_b128 v[60:63], v153 offset:11520
	s_nop 2
	ds_read_b128 v[64:67], v153 offset:11584
	s_waitcnt lgkmcnt(1)
	v_mfma_f32_16x16x32_bf16 v[68:71], v[60:63], v[36:39], 0
	v_mfma_f32_16x16x32_bf16 v[60:63], v[60:63], v[40:43], 0
	s_waitcnt lgkmcnt(0)
	v_mfma_f32_16x16x32_bf16 v[98:101], v[64:67], v[32:35], v[68:71]
	v_mfma_f32_16x16x32_bf16 v[60:63], v[64:67], v[44:47], v[60:63]
	ds_read_b128 v[64:67], v153 offset:13824
	s_nop 2
	ds_read_b128 v[68:71], v153 offset:13888
	s_waitcnt lgkmcnt(1)
	v_mfma_f32_16x16x32_bf16 v[72:75], v[64:67], v[36:39], 0
	v_mfma_f32_16x16x32_bf16 v[64:67], v[64:67], v[40:43], 0
	s_waitcnt lgkmcnt(0)
	v_mfma_f32_16x16x32_bf16 v[102:105], v[68:71], v[32:35], v[72:75]
	v_mfma_f32_16x16x32_bf16 v[64:67], v[68:71], v[44:47], v[64:67]
	ds_read_b128 v[68:71], v153 offset:16128
	s_nop 2
	ds_read_b128 v[72:75], v153 offset:16192
	s_waitcnt lgkmcnt(1)
	v_mfma_f32_16x16x32_bf16 v[76:79], v[68:71], v[36:39], 0
	v_mfma_f32_16x16x32_bf16 v[68:71], v[68:71], v[40:43], 0
	s_waitcnt lgkmcnt(0)
	v_mfma_f32_16x16x32_bf16 v[106:109], v[72:75], v[32:35], v[76:79]
	v_mfma_f32_16x16x32_bf16 v[68:71], v[72:75], v[44:47], v[68:71]
	ds_read_b128 v[72:75], v153 offset:18432
	s_nop 2
	ds_read_b128 v[76:79], v153 offset:18496
	s_waitcnt lgkmcnt(1)
	v_mfma_f32_16x16x32_bf16 v[80:83], v[72:75], v[36:39], 0
	v_mfma_f32_16x16x32_bf16 v[72:75], v[72:75], v[40:43], 0
	s_waitcnt lgkmcnt(0)
	v_mfma_f32_16x16x32_bf16 v[110:113], v[76:79], v[32:35], v[80:83]
	v_mfma_f32_16x16x32_bf16 v[72:75], v[76:79], v[44:47], v[72:75]
	ds_read_b128 v[76:79], v153 offset:20736
	s_nop 2
	ds_read_b128 v[80:83], v153 offset:20800
	s_waitcnt lgkmcnt(1)
	v_mfma_f32_16x16x32_bf16 v[114:117], v[76:79], v[36:39], 0
	v_mfma_f32_16x16x32_bf16 v[76:79], v[76:79], v[40:43], 0
	s_waitcnt lgkmcnt(0)
	v_mfma_f32_16x16x32_bf16 v[114:117], v[80:83], v[32:35], v[114:117]
	v_mfma_f32_16x16x32_bf16 v[76:79], v[80:83], v[44:47], v[76:79]
	ds_read_b128 v[80:83], v153 offset:23040
	ds_read_b128 v[118:121], v153 offset:23104
	s_waitcnt lgkmcnt(1)
	v_mfma_f32_16x16x32_bf16 v[122:125], v[80:83], v[36:39], 0
	v_mfma_f32_16x16x32_bf16 v[80:83], v[80:83], v[40:43], 0
	s_waitcnt lgkmcnt(0)
	v_mfma_f32_16x16x32_bf16 v[180:183], v[118:121], v[32:35], v[122:125]
	v_mfma_f32_16x16x32_bf16 v[80:83], v[118:121], v[44:47], v[80:83]
	ds_read_b128 v[118:121], v153 offset:25344
	s_nop 2
	ds_read_b128 v[122:125], v153 offset:25408
	s_waitcnt lgkmcnt(1)
	v_mfma_f32_16x16x32_bf16 v[36:39], v[118:121], v[36:39], 0
	s_waitcnt lgkmcnt(0)
	v_mfma_f32_16x16x32_bf16 v[184:187], v[122:125], v[32:35], v[36:39]
	v_mfma_f32_16x16x32_bf16 v[32:35], v[118:121], v[40:43], 0
	v_mfma_f32_16x16x32_bf16 v[32:35], v[122:125], v[44:47], v[32:35]
	ds_read2_b32 v[40:41], v139 offset0:159 offset1:160
	ds_read2_b32 v[42:43], v139 offset0:157 offset1:158
	ds_read2_b32 v[44:45], v139 offset0:143 offset1:144
	ds_read2_b32 v[46:47], v139 offset0:141 offset1:142
	ds_read2_b32 v[136:137], v139 offset0:127 offset1:128
	ds_read2_b32 v[164:165], v139 offset0:125 offset1:126
	ds_read2_b32 v[166:167], v139 offset0:111 offset1:112
	ds_read2_b32 v[168:169], v139 offset0:109 offset1:110
	ds_read2_b32 v[170:171], v139 offset0:95 offset1:96
	ds_read2_b32 v[172:173], v139 offset0:93 offset1:94
	ds_read2_b32 v[38:39], v139 offset0:79 offset1:80
	ds_read2_b32 v[36:37], v139 offset0:77 offset1:78
	ds_read2_b32 v[174:175], v139 offset0:63 offset1:64
	ds_read2_b32 v[176:177], v139 offset0:61 offset1:62
	ds_read2_b32 v[178:179], v139 offset0:47 offset1:48
	ds_read2_b32 v[188:189], v139 offset0:45 offset1:46
	ds_read2_b32 v[190:191], v139 offset0:31 offset1:32
	ds_read2_b32 v[192:193], v139 offset0:29 offset1:30
	ds_read2_b32 v[194:195], v139 offset0:15 offset1:16
	ds_read2_b32 v[196:197], v139 offset0:13 offset1:14
	s_waitcnt lgkmcnt(14)
	v_add_f32_e32 v118, v92, v41
	v_add_f32_e32 v119, v92, v40
	v_add_f32_e32 v41, v84, v118
	v_add_f32_e32 v40, v85, v119
	v_add_f32_e32 v120, v92, v43
	v_add_f32_e32 v121, v92, v42
	v_max3_f32 v84, v41, s7, v40
	v_add_f32_e32 v43, v86, v120
	v_add_f32_e32 v42, v87, v121
	v_add_f32_e32 v122, v92, v45
	v_add_f32_e32 v123, v92, v44
	v_max3_f32 v84, v84, v43, v42
	v_add_f32_e32 v45, v88, v122
	v_add_f32_e32 v44, v89, v123
	v_add_f32_e32 v124, v92, v47
	v_add_f32_e32 v125, v92, v46
	v_max3_f32 v84, v84, v45, v44
	v_add_f32_e32 v47, v90, v124
	v_add_f32_e32 v46, v91, v125
	v_add_f32_e32 v126, v92, v137
	v_add_f32_e32 v127, v92, v136
	v_max3_f32 v84, v84, v47, v46
	v_add_f32_e32 v85, v94, v126
	v_add_f32_e32 v86, v95, v127
	v_add_f32_e32 v136, v92, v165
	v_add_f32_e32 v137, v92, v164
	v_max3_f32 v84, v84, v85, v86
	v_add_f32_e32 v87, v96, v136
	v_add_f32_e32 v88, v97, v137
	s_waitcnt lgkmcnt(13)
	v_add_f32_e32 v163, v92, v167
	v_add_f32_e32 v164, v92, v166
	v_max3_f32 v84, v84, v87, v88
	v_add_f32_e32 v89, v98, v163
	v_add_f32_e32 v90, v99, v164
	s_waitcnt lgkmcnt(12)
	v_add_f32_e32 v165, v92, v169
	v_add_f32_e32 v166, v92, v168
	v_max3_f32 v84, v84, v89, v90
	v_add_f32_e32 v91, v100, v165
	v_add_f32_e32 v93, v101, v166
	s_waitcnt lgkmcnt(11)
	v_add_f32_e32 v167, v92, v171
	v_add_f32_e32 v168, v92, v170
	v_max3_f32 v84, v84, v91, v93
	v_add_f32_e32 v94, v102, v167
	v_add_f32_e32 v95, v103, v168
	s_waitcnt lgkmcnt(10)
	v_add_f32_e32 v169, v92, v173
	v_add_f32_e32 v170, v92, v172
	v_max3_f32 v84, v84, v94, v95
	v_add_f32_e32 v96, v104, v169
	v_add_f32_e32 v97, v105, v170
	s_waitcnt lgkmcnt(9)
	v_add_f32_e32 v98, v92, v39
	v_add_f32_e32 v99, v92, v38
	v_max3_f32 v84, v84, v96, v97
	v_add_f32_e32 v98, v106, v98
	v_add_f32_e32 v99, v107, v99
	s_waitcnt lgkmcnt(8)
	v_add_f32_e32 v100, v92, v37
	v_add_f32_e32 v101, v92, v36
	v_max3_f32 v84, v84, v98, v99
	v_add_f32_e32 v100, v108, v100
	v_add_f32_e32 v101, v109, v101
	s_waitcnt lgkmcnt(7)
	v_add_f32_e32 v171, 0, v175
	v_add_f32_e32 v172, 0, v174
	v_max3_f32 v84, v84, v100, v101
	v_add_f32_e32 v198, v110, v171
	v_add_f32_e32 v199, v111, v172
	s_waitcnt lgkmcnt(6)
	v_add_f32_e32 v173, 0, v177
	v_add_f32_e32 v174, 0, v176
	v_max3_f32 v84, v84, v198, v199
	v_add_f32_e32 v210, v112, v173
	v_add_f32_e32 v211, v113, v174
	s_waitcnt lgkmcnt(5)
	v_add_f32_e32 v175, 0, v179
	v_add_f32_e32 v176, 0, v178
	s_waitcnt lgkmcnt(3)
	v_add_f32_e32 v179, 0, v191
	v_max3_f32 v84, v84, v210, v211
	v_add_f32_e32 v212, v114, v175
	v_add_f32_e32 v213, v115, v176
	v_add_f32_e32 v177, 0, v189
	v_add_f32_e32 v178, 0, v188
	v_add_f32_e32 v191, v180, v179
	v_add_f32_e32 v180, 0, v190
	v_max3_f32 v84, v84, v212, v213
	v_add_f32_e32 v189, v116, v177
	v_add_f32_e32 v188, v117, v178
	v_add_f32_e32 v190, v181, v180
	s_waitcnt lgkmcnt(2)
	v_add_f32_e32 v181, 0, v193
	s_waitcnt lgkmcnt(1)
	v_add_f32_e32 v102, 0, v195
	v_max3_f32 v84, v84, v189, v188
	v_add_f32_e32 v193, v182, v181
	v_add_f32_e32 v182, 0, v192
	v_add_f32_e32 v184, v184, v102
	v_add_f32_e32 v102, 0, v194
	v_max3_f32 v84, v84, v191, v190
	v_add_f32_e32 v183, v183, v182
	v_add_f32_e32 v185, v185, v102
	s_waitcnt lgkmcnt(0)
	v_add_f32_e32 v102, 0, v197
	v_max3_f32 v84, v84, v193, v183
	v_add_f32_e32 v186, v186, v102
	v_add_f32_e32 v102, 0, v196
	v_max3_f32 v84, v84, v184, v185
	v_add_f32_e32 v187, v187, v102
	v_max3_f32 v84, v84, v186, v187
	ds_bpermute_b32 v102, v140, v84
	v_add_f32_e32 v52, v52, v118
	v_add_f32_e32 v53, v53, v119
	v_add_f32_e32 v54, v54, v120
	v_add_f32_e32 v55, v55, v121
	s_waitcnt lgkmcnt(0)
	v_max_f32_e32 v102, v102, v102
	v_max_f32_e32 v84, v84, v102
	ds_bpermute_b32 v102, v141, v84
	v_add_f32_e32 v56, v56, v122
	v_add_f32_e32 v57, v57, v123
	v_add_f32_e32 v58, v58, v124
	v_add_f32_e32 v59, v59, v125
	s_waitcnt lgkmcnt(0)
	v_max3_f32 v192, v84, v102, v133
	v_sub_f32_e32 v41, v41, v192
	v_exp_f32_e32 v110, v41
	v_sub_f32_e32 v40, v40, v192
	v_exp_f32_e32 v111, v40
	v_sub_f32_e32 v84, v187, v192
	v_add_f32_e32 v41, 0, v110
	v_exp_f32_e32 v84, v84
	v_add_f32_e32 v40, v111, v41
	v_sub_f32_e32 v41, v43, v192
	v_exp_f32_e32 v112, v41
	v_sub_f32_e32 v41, v42, v192
	v_exp_f32_e32 v113, v41
	v_sub_f32_e32 v41, v45, v192
	v_exp_f32_e32 v114, v41
	v_sub_f32_e32 v41, v44, v192
	v_exp_f32_e32 v115, v41
	v_sub_f32_e32 v41, v47, v192
	v_add_f32_e32 v40, v112, v40
	v_exp_f32_e32 v116, v41
	v_sub_f32_e32 v41, v46, v192
	v_add_f32_e32 v40, v113, v40
	v_exp_f32_e32 v117, v41
	v_sub_f32_e32 v41, v85, v192
	v_add_f32_e32 v40, v114, v40
	v_exp_f32_e32 v102, v41
	v_sub_f32_e32 v41, v86, v192
	v_add_f32_e32 v40, v115, v40
	v_exp_f32_e32 v103, v41
	v_sub_f32_e32 v41, v87, v192
	v_add_f32_e32 v40, v116, v40
	v_exp_f32_e32 v104, v41
	v_sub_f32_e32 v41, v88, v192
	v_add_f32_e32 v40, v117, v40
	v_exp_f32_e32 v105, v41
	v_sub_f32_e32 v41, v89, v192
	v_add_f32_e32 v40, v102, v40
	v_exp_f32_e32 v106, v41
	v_sub_f32_e32 v41, v90, v192
	v_add_f32_e32 v40, v103, v40
	v_exp_f32_e32 v107, v41
	v_sub_f32_e32 v41, v91, v192
	v_add_f32_e32 v40, v104, v40
	v_exp_f32_e32 v108, v41
	v_sub_f32_e32 v41, v93, v192
	v_add_f32_e32 v40, v105, v40
	v_exp_f32_e32 v109, v41
	v_sub_f32_e32 v41, v94, v192
	v_add_f32_e32 v40, v106, v40
	v_exp_f32_e32 v94, v41
	v_sub_f32_e32 v41, v95, v192
	v_add_f32_e32 v40, v107, v40
	v_exp_f32_e32 v95, v41
	v_sub_f32_e32 v41, v96, v192
	v_add_f32_e32 v40, v108, v40
	v_exp_f32_e32 v96, v41
	v_sub_f32_e32 v41, v97, v192
	v_add_f32_e32 v40, v109, v40
	v_exp_f32_e32 v97, v41
	v_sub_f32_e32 v41, v98, v192
	v_add_f32_e32 v40, v94, v40
	v_exp_f32_e32 v98, v41
	v_sub_f32_e32 v41, v99, v192
	v_add_f32_e32 v40, v95, v40
	v_exp_f32_e32 v99, v41
	v_sub_f32_e32 v41, v100, v192
	v_add_f32_e32 v40, v96, v40
	v_exp_f32_e32 v100, v41
	v_sub_f32_e32 v41, v101, v192
	v_add_f32_e32 v40, v97, v40
	v_exp_f32_e32 v101, v41
	v_sub_f32_e32 v41, v198, v192
	v_add_f32_e32 v40, v98, v40
	v_exp_f32_e32 v85, v41
	v_sub_f32_e32 v41, v199, v192
	v_add_f32_e32 v40, v99, v40
	v_exp_f32_e32 v86, v41
	v_sub_f32_e32 v41, v210, v192
	v_add_f32_e32 v40, v100, v40
	v_exp_f32_e32 v87, v41
	v_sub_f32_e32 v41, v211, v192
	v_add_f32_e32 v40, v101, v40
	v_exp_f32_e32 v88, v41
	v_sub_f32_e32 v41, v212, v192
	v_add_f32_e32 v40, v85, v40
	v_exp_f32_e32 v89, v41
	v_sub_f32_e32 v41, v213, v192
	v_add_f32_e32 v40, v86, v40
	v_exp_f32_e32 v90, v41
	v_sub_f32_e32 v41, v189, v192
	v_add_f32_e32 v40, v87, v40
	v_exp_f32_e32 v91, v41
	v_sub_f32_e32 v41, v188, v192
	v_add_f32_e32 v40, v88, v40
	v_exp_f32_e32 v93, v41
	v_sub_f32_e32 v41, v191, v192
	v_add_f32_e32 v40, v89, v40
	v_exp_f32_e32 v41, v41
	v_sub_f32_e32 v42, v190, v192
	v_add_f32_e32 v40, v90, v40
	v_exp_f32_e32 v42, v42
	v_sub_f32_e32 v43, v193, v192
	v_add_f32_e32 v40, v91, v40
	v_exp_f32_e32 v43, v43
	v_sub_f32_e32 v44, v183, v192
	v_add_f32_e32 v40, v93, v40
	v_exp_f32_e32 v44, v44
	v_sub_f32_e32 v45, v184, v192
	v_add_f32_e32 v40, v41, v40
	v_exp_f32_e32 v45, v45
	v_sub_f32_e32 v46, v185, v192
	v_add_f32_e32 v40, v42, v40
	v_exp_f32_e32 v46, v46
	v_sub_f32_e32 v47, v186, v192
	v_add_f32_e32 v40, v43, v40
	v_exp_f32_e32 v47, v47
	v_add_f32_e32 v40, v44, v40
	v_add_f32_e32 v40, v45, v40
	v_add_f32_e32 v40, v46, v40
	v_add_f32_e32 v40, v47, v40
	v_add_f32_e32 v40, v84, v40
	ds_bpermute_b32 v183, v140, v40
	v_add_f32_e32 v60, v60, v126
	v_add_f32_e32 v61, v61, v127
	v_add_f32_e32 v62, v62, v136
	v_add_f32_e32 v63, v63, v137
	s_waitcnt lgkmcnt(0)
	v_add_f32_e32 v40, v40, v183
	ds_bpermute_b32 v183, v141, v40
	v_add_f32_e32 v64, v64, v163
	v_add_f32_e32 v119, v65, v164
	v_add_f32_e32 v120, v67, v166
	v_add_f32_e32 v121, v68, v167
	s_waitcnt lgkmcnt(0)
	v_add_f32_e32 v40, v40, v183
	v_fma_f32 v183, v162, s6, -v192
	v_exp_f32_e32 v183, v183
	v_add_f32_e32 v122, v69, v168
	v_add_f32_e32 v123, v70, v169
	v_add_f32_e32 v124, v71, v170
	v_add_f32_e32 v40, v183, v40
	v_div_scale_f32 v183, s[0:1], v40, v40, 1.0
	v_rcp_f32_e32 v184, v183
	v_add_f32_e32 v39, 0, v39
	v_add_f32_e32 v38, 0, v38
	v_add_f32_e32 v39, v72, v39
	v_fma_f32 v185, -v183, v184, 1.0
	v_fmac_f32_e32 v184, v185, v184
	v_div_scale_f32 v185, vcc, 1.0, v40, 1.0
	v_mul_f32_e32 v186, v185, v184
	v_fma_f32 v187, -v183, v186, v185
	v_fmac_f32_e32 v186, v187, v184
	v_fma_f32 v183, -v183, v186, v185
	v_div_fmas_f32 v183, v183, v184, v186
	ds_read2_b32 v[184:185], v139 offset0:175 offset1:176
	ds_read2_b32 v[186:187], v139 offset0:173 offset1:174
	v_div_fixup_f32 v40, v183, v40, 1.0
	v_add_f32_e32 v38, v73, v38
	v_add_f32_e32 v37, 0, v37
	s_waitcnt lgkmcnt(1)
	v_add_f32_e32 v183, v92, v185
	v_add_f32_e32 v48, v48, v183
	v_add_f32_e32 v183, v92, v184
	s_waitcnt lgkmcnt(0)
	v_add_f32_e32 v184, v92, v187
	v_add_f32_e32 v49, v49, v183
	v_add_f32_e32 v50, v50, v184
	v_add_f32_e32 v184, v92, v186
	v_max3_f32 v183, v48, s7, v49
	v_add_f32_e32 v51, v51, v184
	v_max3_f32 v183, v183, v50, v51
	v_max3_f32 v118, v183, v52, v53
	v_max3_f32 v118, v118, v54, v55
	v_max3_f32 v118, v118, v56, v57
	v_max3_f32 v118, v118, v58, v59
	v_max3_f32 v118, v118, v60, v61
	v_max3_f32 v118, v118, v62, v63
	v_max3_f32 v65, v118, v64, v119
	v_add_f32_e32 v118, v66, v165
	v_max3_f32 v65, v65, v118, v120
	v_max3_f32 v65, v65, v121, v122
	v_max3_f32 v65, v65, v123, v124
	v_add_f32_e32 v36, 0, v36
	v_max3_f32 v65, v65, v39, v38
	v_add_f32_e32 v37, v74, v37
	v_add_f32_e32 v36, v75, v36
	v_max3_f32 v65, v65, v37, v36
	v_add_f32_e32 v125, v76, v171
	v_add_f32_e32 v126, v77, v172
	v_max3_f32 v65, v65, v125, v126
	v_add_f32_e32 v127, v78, v173
	v_add_f32_e32 v136, v79, v174
	v_max3_f32 v65, v65, v127, v136
	v_add_f32_e32 v137, v80, v175
	v_add_f32_e32 v81, v81, v176
	v_max3_f32 v65, v65, v137, v81
	v_add_f32_e32 v82, v82, v177
	v_add_f32_e32 v83, v83, v178
	v_max3_f32 v65, v65, v82, v83
	v_add_f32_e32 v32, v32, v179
	v_add_f32_e32 v163, v33, v180
	v_max3_f32 v33, v65, v32, v163
	v_add_f32_e32 v164, v34, v181
	v_add_f32_e32 v165, v35, v182
	v_max3_f32 v33, v33, v164, v165
	ds_bpermute_b32 v34, v140, v33
	v_cvt_pk_bf16_f32 v110, v110, v111
	v_cvt_pk_bf16_f32 v111, v112, v113
	v_cvt_pk_bf16_f32 v112, v114, v115
	v_cvt_pk_bf16_f32 v113, v116, v117
	s_waitcnt lgkmcnt(0)
	v_max_f32_e32 v34, v34, v34
	v_max_f32_e32 v33, v33, v34
	ds_bpermute_b32 v34, v141, v33
	s_waitcnt lgkmcnt(0)
	v_max3_f32 v166, v33, v34, v133
	v_sub_f32_e32 v33, v48, v166
	v_exp_f32_e32 v73, v33
	v_sub_f32_e32 v34, v49, v166
	v_exp_f32_e32 v74, v34
	v_sub_f32_e32 v34, v50, v166
	v_exp_f32_e32 v75, v34
	v_sub_f32_e32 v34, v51, v166
	v_exp_f32_e32 v76, v34
	v_sub_f32_e32 v34, v52, v166
	v_add_f32_e32 v33, 0, v73
	v_exp_f32_e32 v77, v34
	v_sub_f32_e32 v34, v53, v166
	v_add_f32_e32 v33, v74, v33
	v_exp_f32_e32 v78, v34
	v_sub_f32_e32 v34, v54, v166
	v_add_f32_e32 v33, v75, v33
	v_exp_f32_e32 v79, v34
	v_sub_f32_e32 v34, v55, v166
	v_add_f32_e32 v33, v76, v33
	v_exp_f32_e32 v80, v34
	v_sub_f32_e32 v34, v56, v166
	v_add_f32_e32 v33, v77, v33
	v_exp_f32_e32 v65, v34
	v_sub_f32_e32 v34, v57, v166
	v_add_f32_e32 v33, v78, v33
	v_exp_f32_e32 v66, v34
	v_sub_f32_e32 v34, v58, v166
	v_add_f32_e32 v33, v79, v33
	v_exp_f32_e32 v67, v34
	v_sub_f32_e32 v34, v59, v166
	v_add_f32_e32 v33, v80, v33
	v_exp_f32_e32 v68, v34
	v_sub_f32_e32 v34, v60, v166
	v_add_f32_e32 v33, v65, v33
	v_exp_f32_e32 v69, v34
	v_sub_f32_e32 v34, v61, v166
	v_add_f32_e32 v33, v66, v33
	v_exp_f32_e32 v70, v34
	v_sub_f32_e32 v34, v62, v166
	v_add_f32_e32 v33, v67, v33
	v_exp_f32_e32 v71, v34
	v_sub_f32_e32 v34, v63, v166
	v_add_f32_e32 v33, v68, v33
	v_exp_f32_e32 v72, v34
	v_sub_f32_e32 v34, v64, v166
	v_add_f32_e32 v33, v69, v33
	v_exp_f32_e32 v57, v34
	v_sub_f32_e32 v34, v119, v166
	v_add_f32_e32 v33, v70, v33
	v_exp_f32_e32 v58, v34
	v_sub_f32_e32 v34, v118, v166
	v_add_f32_e32 v33, v71, v33
	v_exp_f32_e32 v59, v34
	v_sub_f32_e32 v34, v120, v166
	v_add_f32_e32 v33, v72, v33
	v_exp_f32_e32 v60, v34
	v_sub_f32_e32 v34, v121, v166
	v_add_f32_e32 v33, v57, v33
	v_exp_f32_e32 v61, v34
	v_sub_f32_e32 v34, v122, v166
	v_add_f32_e32 v33, v58, v33
	v_exp_f32_e32 v62, v34
	v_sub_f32_e32 v34, v123, v166
	v_add_f32_e32 v33, v59, v33
	v_exp_f32_e32 v63, v34
	v_sub_f32_e32 v34, v124, v166
	v_add_f32_e32 v33, v60, v33
	v_exp_f32_e32 v64, v34
	v_sub_f32_e32 v34, v39, v166
	v_add_f32_e32 v33, v61, v33
	v_exp_f32_e32 v49, v34
	v_sub_f32_e32 v34, v38, v166
	v_add_f32_e32 v33, v62, v33
	v_exp_f32_e32 v50, v34
	v_sub_f32_e32 v34, v37, v166
	v_add_f32_e32 v33, v63, v33
	v_exp_f32_e32 v51, v34
	v_sub_f32_e32 v34, v36, v166
	v_add_f32_e32 v33, v64, v33
	v_exp_f32_e32 v52, v34
	v_sub_f32_e32 v34, v125, v166
	v_add_f32_e32 v33, v49, v33
	v_exp_f32_e32 v53, v34
	v_sub_f32_e32 v34, v126, v166
	v_add_f32_e32 v33, v50, v33
	v_exp_f32_e32 v54, v34
	v_sub_f32_e32 v34, v127, v166
	v_add_f32_e32 v33, v51, v33
	v_exp_f32_e32 v55, v34
	v_sub_f32_e32 v34, v136, v166
	v_add_f32_e32 v33, v52, v33
	v_exp_f32_e32 v56, v34
	v_add_f32_e32 v33, v53, v33
	v_add_f32_e32 v33, v54, v33
	v_add_f32_e32 v33, v55, v33
	v_add_f32_e32 v34, v56, v33
	v_sub_f32_e32 v33, v137, v166
	v_exp_f32_e32 v33, v33
	v_sub_f32_e32 v32, v32, v166
	v_sub_f32_e32 v39, v164, v166
	v_exp_f32_e32 v39, v39
	v_add_f32_e32 v35, v33, v34
	v_sub_f32_e32 v34, v81, v166
	v_exp_f32_e32 v34, v34
	v_sub_f32_e32 v48, v165, v166
	v_exp_f32_e32 v48, v48
	v_cvt_pk_bf16_f32 v74, v73, v74
	v_add_f32_e32 v36, v34, v35
	v_sub_f32_e32 v35, v82, v166
	v_exp_f32_e32 v35, v35
	v_cvt_pk_bf16_f32 v75, v75, v76
	v_cvt_pk_bf16_f32 v76, v77, v78
	v_cvt_pk_bf16_f32 v77, v79, v80
	ds_read_b128 v[172:175], v142 offset:62272
	v_add_f32_e32 v37, v35, v36
	v_sub_f32_e32 v36, v83, v166
	v_exp_f32_e32 v36, v36
	s_nop 0
	v_add_f32_e32 v38, v36, v37
	v_exp_f32_e32 v37, v32
	s_nop 0
	v_add_f32_e32 v32, v37, v38
	v_sub_f32_e32 v38, v163, v166
	v_exp_f32_e32 v38, v38
	s_nop 0
	v_add_f32_e32 v32, v38, v32
	v_add_f32_e32 v32, v39, v32
	v_add_f32_e32 v32, v48, v32
	ds_bpermute_b32 v81, v140, v32
	s_waitcnt lgkmcnt(0)
	v_add_f32_e32 v32, v32, v81
	ds_bpermute_b32 v81, v141, v32
	s_waitcnt lgkmcnt(0)
	v_add_f32_e32 v32, v32, v81
	v_fma_f32 v81, v162, s6, -v166
	v_exp_f32_e32 v81, v81
	ds_read_b128 v[164:167], v142 offset:53824
	s_waitcnt lgkmcnt(0)
	v_mfma_f32_16x16x32_bf16 v[168:171], v[164:167], v[110:113], 0
	v_add_f32_e32 v32, v81, v32
	v_div_scale_f32 v81, s[0:1], v32, v32, 1.0
	v_rcp_f32_e32 v82, v81
	v_mfma_f32_16x16x32_bf16 v[164:167], v[164:167], v[74:77], 0
	v_fma_f32 v83, -v81, v82, 1.0
	v_fmac_f32_e32 v82, v83, v82
	v_div_scale_f32 v83, vcc, 1.0, v32, 1.0
	v_mul_f32_e32 v118, v83, v82
	v_fma_f32 v119, -v81, v118, v83
	v_fmac_f32_e32 v118, v119, v82
	v_fma_f32 v81, -v81, v118, v83
	v_div_fmas_f32 v81, v81, v82, v118
	v_div_fixup_f32 v32, v81, v32, 1.0
	ds_read_b128 v[78:81], v142 offset:36928
	ds_read_b128 v[118:121], v142 offset:45376
	v_cvt_pk_bf16_f32 v102, v102, v103
	v_cvt_pk_bf16_f32 v103, v104, v105
	v_cvt_pk_bf16_f32 v104, v106, v107
	v_cvt_pk_bf16_f32 v105, v108, v109
	v_cvt_pk_bf16_f32 v66, v65, v66
	v_cvt_pk_bf16_f32 v67, v67, v68
	v_cvt_pk_bf16_f32 v68, v69, v70
	v_cvt_pk_bf16_f32 v69, v71, v72
	ds_read_b128 v[70:73], v142 offset:36992
	s_waitcnt lgkmcnt(2)
	v_mfma_f32_16x16x32_bf16 v[114:117], v[78:81], v[110:113], 0
	v_mfma_f32_16x16x32_bf16 v[78:81], v[78:81], v[74:77], 0
	s_waitcnt lgkmcnt(0)
	v_mfma_f32_16x16x32_bf16 v[106:109], v[70:73], v[102:105], v[114:117]
	v_mfma_f32_16x16x32_bf16 v[70:73], v[70:73], v[66:69], v[78:81]
	s_nop 4
	ds_read_b128 v[78:81], v142 offset:45440
	v_mfma_f32_16x16x32_bf16 v[122:125], v[118:121], v[110:113], 0
	v_mfma_f32_16x16x32_bf16 v[118:121], v[118:121], v[74:77], 0
	s_waitcnt lgkmcnt(0)
	v_mfma_f32_16x16x32_bf16 v[114:117], v[78:81], v[102:105], v[122:125]
	v_mfma_f32_16x16x32_bf16 v[78:81], v[78:81], v[66:69], v[118:121]
	s_nop 4
	ds_read_b128 v[118:121], v142 offset:53888
	s_waitcnt lgkmcnt(0)
	v_mfma_f32_16x16x32_bf16 v[122:125], v[118:121], v[102:105], v[168:171]
	v_mfma_f32_16x16x32_bf16 v[118:121], v[118:121], v[66:69], v[164:167]
	s_nop 2
	ds_read_b128 v[164:167], v142 offset:62336
	v_mfma_f32_16x16x32_bf16 v[74:77], v[172:175], v[74:77], 0
	s_waitcnt lgkmcnt(0)
	v_mfma_f32_16x16x32_bf16 v[66:69], v[164:167], v[66:69], v[74:77]
	v_cvt_pk_bf16_f32 v74, v94, v95
	v_cvt_pk_bf16_f32 v75, v96, v97
	v_cvt_pk_bf16_f32 v76, v98, v99
	v_cvt_pk_bf16_f32 v77, v100, v101
	v_cvt_pk_bf16_f32 v58, v57, v58
	v_cvt_pk_bf16_f32 v59, v59, v60
	v_cvt_pk_bf16_f32 v60, v61, v62
	v_cvt_pk_bf16_f32 v61, v63, v64
	ds_read_b128 v[62:65], v142 offset:37056
	v_mfma_f32_16x16x32_bf16 v[110:113], v[172:175], v[110:113], 0
	v_mfma_f32_16x16x32_bf16 v[102:105], v[164:167], v[102:105], v[110:113]
	s_nop 6
	ds_read_b128 v[110:113], v142 offset:62400
	s_waitcnt lgkmcnt(1)
	v_mfma_f32_16x16x32_bf16 v[94:97], v[62:65], v[74:77], v[106:109]
	v_mfma_f32_16x16x32_bf16 v[62:65], v[62:65], v[58:61], v[70:73]
	s_nop 2
	ds_read_b128 v[70:73], v142 offset:45504
	s_waitcnt lgkmcnt(0)
	v_mfma_f32_16x16x32_bf16 v[98:101], v[70:73], v[74:77], v[114:117]
	v_mfma_f32_16x16x32_bf16 v[70:73], v[70:73], v[58:61], v[78:81]
	s_nop 2
	ds_read_b128 v[78:81], v142 offset:53952
	s_waitcnt lgkmcnt(0)
	v_mfma_f32_16x16x32_bf16 v[106:109], v[78:81], v[74:77], v[122:125]
	v_mfma_f32_16x16x32_bf16 v[78:81], v[78:81], v[58:61], v[118:121]
	v_mfma_f32_16x16x32_bf16 v[58:61], v[110:113], v[58:61], v[66:69]
	v_cvt_pk_bf16_f32 v66, v85, v86
	v_cvt_pk_bf16_f32 v67, v87, v88
	v_cvt_pk_bf16_f32 v68, v89, v90
	v_cvt_pk_bf16_f32 v69, v91, v93
	v_cvt_pk_bf16_f32 v50, v49, v50
	v_cvt_pk_bf16_f32 v51, v51, v52
	v_cvt_pk_bf16_f32 v52, v53, v54
	v_cvt_pk_bf16_f32 v53, v55, v56
	ds_read_b128 v[54:57], v142 offset:37120
	s_waitcnt lgkmcnt(0)
	v_mfma_f32_16x16x32_bf16 v[86:89], v[54:57], v[66:69], v[94:97]
	v_mfma_f32_16x16x32_bf16 v[54:57], v[54:57], v[50:53], v[62:65]
	s_nop 2
	ds_read_b128 v[62:65], v142 offset:45568
	s_waitcnt lgkmcnt(0)
	v_mfma_f32_16x16x32_bf16 v[94:97], v[62:65], v[66:69], v[98:101]
	v_mfma_f32_16x16x32_bf16 v[62:65], v[62:65], v[50:53], v[70:73]
	s_nop 2
	ds_read_b128 v[70:73], v142 offset:54016
	s_waitcnt lgkmcnt(0)
	v_mfma_f32_16x16x32_bf16 v[98:101], v[70:73], v[66:69], v[106:109]
	v_mfma_f32_16x16x32_bf16 v[70:73], v[70:73], v[50:53], v[78:81]
	s_nop 2
	ds_read_b128 v[78:81], v142 offset:62464
	v_cvt_pk_bf16_f32 v42, v41, v42
	v_cvt_pk_bf16_f32 v43, v43, v44
	v_cvt_pk_bf16_f32 v44, v45, v46
	v_cvt_pk_bf16_f32 v45, v47, v84
	v_cvt_pk_bf16_f32 v34, v33, v34
	v_cvt_pk_bf16_f32 v35, v35, v36
	v_cvt_pk_bf16_f32 v36, v37, v38
	v_cvt_pk_bf16_f32 v37, v39, v48
	ds_read_b128 v[46:49], v142 offset:37184
	s_waitcnt lgkmcnt(1)
	v_mfma_f32_16x16x32_bf16 v[50:53], v[78:81], v[50:53], v[58:61]
	v_or_b32_e32 v38, 32, v132
	v_ashrrev_i32_e32 v39, 31, v38
	v_lshlrev_b64 v[38:39], 12, v[38:39]
	s_waitcnt lgkmcnt(0)
	v_mfma_f32_16x16x32_bf16 v[58:61], v[46:49], v[42:45], v[86:89]
	v_lshl_add_u64 v[38:39], v[134:135], 0, v[38:39]
	s_nop 6
	v_mfma_f32_16x16x32_bf16 v[46:49], v[46:49], v[34:37], v[54:57]
	s_nop 1
	ds_read_b128 v[54:57], v142 offset:45632
	v_mfma_f32_16x16x32_bf16 v[74:77], v[110:113], v[74:77], v[102:105]
	v_mfma_f32_16x16x32_bf16 v[66:69], v[78:81], v[66:69], v[74:77]
	s_waitcnt lgkmcnt(0)
	v_mfma_f32_16x16x32_bf16 v[74:77], v[54:57], v[42:45], v[94:97]
	v_mfma_f32_16x16x32_bf16 v[54:57], v[54:57], v[34:37], v[62:65]
	s_nop 2
	ds_read_b128 v[62:65], v142 offset:54080
	s_waitcnt lgkmcnt(0)
	v_mfma_f32_16x16x32_bf16 v[78:81], v[62:65], v[42:45], v[98:101]
	v_mfma_f32_16x16x32_bf16 v[62:65], v[62:65], v[34:37], v[70:73]
	s_nop 2
	ds_read_b128 v[70:73], v142 offset:62528
	s_waitcnt lgkmcnt(0)
	v_mfma_f32_16x16x32_bf16 v[34:37], v[70:73], v[34:37], v[50:53]
	v_mfma_f32_16x16x32_bf16 v[42:45], v[70:73], v[42:45], v[66:69]
	v_mul_f32_e32 v58, v40, v58
	v_mul_f32_e32 v59, v40, v59
	v_mul_f32_e32 v60, v40, v60
	v_mul_f32_e32 v61, v40, v61
	v_mul_f32_e32 v74, v40, v74
	v_mul_f32_e32 v75, v40, v75
	v_mul_f32_e32 v76, v40, v76
	v_mul_f32_e32 v77, v40, v77
	v_mul_f32_e32 v78, v40, v78
	v_mul_f32_e32 v79, v40, v79
	v_mul_f32_e32 v80, v40, v80
	v_mul_f32_e32 v81, v40, v81
	v_mul_f32_e32 v42, v40, v42
	v_mul_f32_e32 v43, v40, v43
	v_mul_f32_e32 v44, v40, v44
	v_mul_f32_e32 v45, v40, v45
	v_cvt_pk_bf16_f32 v58, v58, v59
	v_cvt_pk_bf16_f32 v59, v60, v61
	v_cvt_pk_bf16_f32 v60, v74, v75
	v_cvt_pk_bf16_f32 v61, v76, v77
	v_cvt_pk_bf16_f32 v78, v78, v79
	v_cvt_pk_bf16_f32 v79, v80, v81
	v_cvt_pk_bf16_f32 v80, v42, v43
	v_cvt_pk_bf16_f32 v81, v44, v45
	s_nop 1
	v_permlane16_swap_b32_e32 v58, v60
	v_permlane16_swap_b32_e32 v59, v61
	v_permlane16_swap_b32_e32 v78, v80
	v_permlane16_swap_b32_e32 v79, v81
	global_store_dwordx4 v[38:39], v[58:61], off
	global_store_dwordx4 v[38:39], v[78:81], off offset:64
	v_or_b32_e32 v38, 48, v132
	v_ashrrev_i32_e32 v39, 31, v38
	v_lshlrev_b64 v[38:39], 12, v[38:39]
	v_lshl_add_u64 v[38:39], v[134:135], 0, v[38:39]
	v_mul_f32_e32 v46, v32, v46
	v_mul_f32_e32 v47, v32, v47
	v_mul_f32_e32 v48, v32, v48
	v_mul_f32_e32 v49, v32, v49
	v_mul_f32_e32 v54, v32, v54
	v_mul_f32_e32 v55, v32, v55
	v_mul_f32_e32 v56, v32, v56
	v_mul_f32_e32 v57, v32, v57
	v_mul_f32_e32 v62, v32, v62
	v_mul_f32_e32 v63, v32, v63
	v_mul_f32_e32 v64, v32, v64
	v_mul_f32_e32 v65, v32, v65
	v_mul_f32_e32 v34, v32, v34
	v_mul_f32_e32 v35, v32, v35
	v_mul_f32_e32 v36, v32, v36
	v_mul_f32_e32 v37, v32, v37
	v_cvt_pk_bf16_f32 v46, v46, v47
	v_cvt_pk_bf16_f32 v47, v48, v49
	v_cvt_pk_bf16_f32 v48, v54, v55
	v_cvt_pk_bf16_f32 v49, v56, v57
	v_cvt_pk_bf16_f32 v62, v62, v63
	v_cvt_pk_bf16_f32 v63, v64, v65
	v_cvt_pk_bf16_f32 v64, v34, v35
	v_cvt_pk_bf16_f32 v65, v36, v37
	s_nop 1
	v_permlane16_swap_b32_e32 v46, v48
	v_permlane16_swap_b32_e32 v47, v49
	v_permlane16_swap_b32_e32 v62, v64
	v_permlane16_swap_b32_e32 v63, v65
	global_store_dwordx4 v[38:39], v[46:49], off
	global_store_dwordx4 v[38:39], v[62:65], off offset:64
	ds_read_b128 v[32:35], v153 offset:9216
	ds_read_b128 v[36:39], v153 offset:9280
	s_waitcnt vmcnt(15) lgkmcnt(1)
	v_mfma_f32_16x16x32_bf16 v[40:43], v[32:35], v[20:23], 0
	s_waitcnt vmcnt(13)
	v_mfma_f32_16x16x32_bf16 v[32:35], v[32:35], v[24:27], 0
	s_waitcnt lgkmcnt(0)
	v_mfma_f32_16x16x32_bf16 v[68:71], v[36:39], v[16:19], v[40:43]
	s_waitcnt vmcnt(12)
	v_mfma_f32_16x16x32_bf16 v[32:35], v[36:39], v[28:31], v[32:35]
	ds_read_b128 v[36:39], v153 offset:11520
	s_nop 0
	ds_read_b128 v[40:43], v153 offset:11584
	s_waitcnt lgkmcnt(1)
	v_mfma_f32_16x16x32_bf16 v[44:47], v[36:39], v[20:23], 0
	v_mfma_f32_16x16x32_bf16 v[36:39], v[36:39], v[24:27], 0
	s_waitcnt lgkmcnt(0)
	v_mfma_f32_16x16x32_bf16 v[72:75], v[40:43], v[16:19], v[44:47]
	v_mfma_f32_16x16x32_bf16 v[36:39], v[40:43], v[28:31], v[36:39]
	ds_read_b128 v[40:43], v153 offset:13824
	s_nop 2
	ds_read_b128 v[44:47], v153 offset:13888
	s_waitcnt lgkmcnt(1)
	v_mfma_f32_16x16x32_bf16 v[48:51], v[40:43], v[20:23], 0
	v_mfma_f32_16x16x32_bf16 v[40:43], v[40:43], v[24:27], 0
	s_waitcnt lgkmcnt(0)
	v_mfma_f32_16x16x32_bf16 v[76:79], v[44:47], v[16:19], v[48:51]
	v_mfma_f32_16x16x32_bf16 v[40:43], v[44:47], v[28:31], v[40:43]
	ds_read_b128 v[44:47], v153 offset:16128
	s_nop 2
	ds_read_b128 v[48:51], v153 offset:16192
	s_waitcnt lgkmcnt(1)
	v_mfma_f32_16x16x32_bf16 v[52:55], v[44:47], v[20:23], 0
	v_mfma_f32_16x16x32_bf16 v[44:47], v[44:47], v[24:27], 0
	s_waitcnt lgkmcnt(0)
	v_mfma_f32_16x16x32_bf16 v[80:83], v[48:51], v[16:19], v[52:55]
	v_mfma_f32_16x16x32_bf16 v[44:47], v[48:51], v[28:31], v[44:47]
	ds_read_b128 v[48:51], v153 offset:18432
	s_nop 2
	ds_read_b128 v[52:55], v153 offset:18496
	s_waitcnt lgkmcnt(1)
	v_mfma_f32_16x16x32_bf16 v[56:59], v[48:51], v[20:23], 0
	v_mfma_f32_16x16x32_bf16 v[48:51], v[48:51], v[24:27], 0
	s_waitcnt lgkmcnt(0)
	v_mfma_f32_16x16x32_bf16 v[84:87], v[52:55], v[16:19], v[56:59]
	v_mfma_f32_16x16x32_bf16 v[48:51], v[52:55], v[28:31], v[48:51]
	ds_read_b128 v[52:55], v153 offset:20736
	s_nop 2
	ds_read_b128 v[56:59], v153 offset:20800
	s_waitcnt lgkmcnt(1)
	v_mfma_f32_16x16x32_bf16 v[60:63], v[52:55], v[20:23], 0
	v_mfma_f32_16x16x32_bf16 v[52:55], v[52:55], v[24:27], 0
	s_waitcnt lgkmcnt(0)
	v_mfma_f32_16x16x32_bf16 v[88:91], v[56:59], v[16:19], v[60:63]
	v_mfma_f32_16x16x32_bf16 v[52:55], v[56:59], v[28:31], v[52:55]
	ds_read_b128 v[56:59], v153 offset:23040
	s_nop 2
	ds_read_b128 v[60:63], v153 offset:23104
	s_waitcnt lgkmcnt(1)
	v_mfma_f32_16x16x32_bf16 v[64:67], v[56:59], v[20:23], 0
	v_mfma_f32_16x16x32_bf16 v[56:59], v[56:59], v[24:27], 0
	s_waitcnt lgkmcnt(0)
	v_mfma_f32_16x16x32_bf16 v[94:97], v[60:63], v[16:19], v[64:67]
	v_mfma_f32_16x16x32_bf16 v[56:59], v[60:63], v[28:31], v[56:59]
	ds_read_b128 v[60:63], v153 offset:25344
	s_nop 2
	ds_read_b128 v[64:67], v153 offset:25408
	s_waitcnt lgkmcnt(1)
	v_mfma_f32_16x16x32_bf16 v[98:101], v[60:63], v[20:23], 0
	v_mfma_f32_16x16x32_bf16 v[60:63], v[60:63], v[24:27], 0
	s_waitcnt lgkmcnt(0)
	v_mfma_f32_16x16x32_bf16 v[98:101], v[64:67], v[16:19], v[98:101]
	v_mfma_f32_16x16x32_bf16 v[60:63], v[64:67], v[28:31], v[60:63]
	ds_read_b128 v[64:67], v153 offset:27648
	ds_read_b128 v[102:105], v153 offset:27712
	s_waitcnt lgkmcnt(1)
	v_mfma_f32_16x16x32_bf16 v[106:109], v[64:67], v[20:23], 0
	v_mfma_f32_16x16x32_bf16 v[64:67], v[64:67], v[24:27], 0
	s_waitcnt lgkmcnt(0)
	v_mfma_f32_16x16x32_bf16 v[164:167], v[102:105], v[16:19], v[106:109]
	v_mfma_f32_16x16x32_bf16 v[64:67], v[102:105], v[28:31], v[64:67]
	ds_read_b128 v[102:105], v153 offset:29952
	s_nop 2
	ds_read_b128 v[106:109], v153 offset:30016
	s_waitcnt lgkmcnt(1)
	v_mfma_f32_16x16x32_bf16 v[20:23], v[102:105], v[20:23], 0
	s_waitcnt lgkmcnt(0)
	v_mfma_f32_16x16x32_bf16 v[168:171], v[106:109], v[16:19], v[20:23]
	v_mfma_f32_16x16x32_bf16 v[16:19], v[102:105], v[24:27], 0
	v_mfma_f32_16x16x32_bf16 v[16:19], v[106:109], v[28:31], v[16:19]
	ds_read2_b32 v[24:25], v139 offset0:159 offset1:160
	ds_read2_b32 v[26:27], v139 offset0:157 offset1:158
	ds_read2_b32 v[28:29], v139 offset0:143 offset1:144
	ds_read2_b32 v[30:31], v139 offset0:141 offset1:142
	ds_read2_b32 v[112:113], v139 offset0:127 offset1:128
	ds_read2_b32 v[114:115], v139 offset0:125 offset1:126
	ds_read2_b32 v[22:23], v139 offset0:111 offset1:112
	ds_read2_b32 v[20:21], v139 offset0:109 offset1:110
	ds_read2_b32 v[116:117], v139 offset0:95 offset1:96
	ds_read2_b32 v[118:119], v139 offset0:93 offset1:94
	ds_read2_b32 v[120:121], v139 offset0:79 offset1:80
	ds_read2_b32 v[122:123], v139 offset0:77 offset1:78
	ds_read2_b32 v[124:125], v139 offset0:63 offset1:64
	ds_read2_b32 v[126:127], v139 offset0:61 offset1:62
	ds_read2_b32 v[136:137], v139 offset0:47 offset1:48
	ds_read2_b32 v[172:173], v139 offset0:45 offset1:46
	ds_read2_b32 v[174:175], v139 offset0:31 offset1:32
	ds_read2_b32 v[176:177], v139 offset0:29 offset1:30
	ds_read2_b32 v[178:179], v139 offset0:15 offset1:16
	ds_read2_b32 v[180:181], v139 offset0:13 offset1:14
	s_waitcnt lgkmcnt(14)
	v_add_f32_e32 v102, v92, v25
	v_add_f32_e32 v103, v92, v24
	v_add_f32_e32 v25, v68, v102
	v_add_f32_e32 v24, v69, v103
	v_add_f32_e32 v104, v92, v27
	v_add_f32_e32 v105, v92, v26
	v_max3_f32 v68, v25, s7, v24
	v_add_f32_e32 v27, v70, v104
	v_add_f32_e32 v26, v71, v105
	v_add_f32_e32 v106, v92, v29
	v_add_f32_e32 v107, v92, v28
	v_max3_f32 v68, v68, v27, v26
	v_add_f32_e32 v29, v72, v106
	v_add_f32_e32 v28, v73, v107
	v_add_f32_e32 v108, v92, v31
	v_add_f32_e32 v109, v92, v30
	v_max3_f32 v68, v68, v29, v28
	v_add_f32_e32 v31, v74, v108
	v_add_f32_e32 v30, v75, v109
	v_add_f32_e32 v110, v92, v113
	v_add_f32_e32 v111, v92, v112
	v_max3_f32 v68, v68, v31, v30
	v_add_f32_e32 v69, v76, v110
	v_add_f32_e32 v70, v77, v111
	v_add_f32_e32 v112, v92, v115
	v_add_f32_e32 v113, v92, v114
	v_max3_f32 v68, v68, v69, v70
	v_add_f32_e32 v71, v78, v112
	v_add_f32_e32 v72, v79, v113
	s_waitcnt lgkmcnt(13)
	v_add_f32_e32 v73, v92, v23
	v_add_f32_e32 v74, v92, v22
	v_max3_f32 v68, v68, v71, v72
	v_add_f32_e32 v73, v80, v73
	v_add_f32_e32 v74, v81, v74
	s_waitcnt lgkmcnt(12)
	v_add_f32_e32 v75, v92, v21
	v_add_f32_e32 v76, v92, v20
	v_max3_f32 v68, v68, v73, v74
	v_add_f32_e32 v75, v82, v75
	v_add_f32_e32 v76, v83, v76
	s_waitcnt lgkmcnt(11)
	v_add_f32_e32 v114, 0, v117
	v_add_f32_e32 v115, 0, v116
	v_max3_f32 v68, v68, v75, v76
	v_add_f32_e32 v77, v84, v114
	v_add_f32_e32 v78, v85, v115
	s_waitcnt lgkmcnt(10)
	v_add_f32_e32 v116, 0, v119
	v_add_f32_e32 v117, 0, v118
	v_max3_f32 v68, v68, v77, v78
	v_add_f32_e32 v79, v86, v116
	v_add_f32_e32 v80, v87, v117
	s_waitcnt lgkmcnt(9)
	v_add_f32_e32 v118, 0, v121
	v_add_f32_e32 v119, 0, v120
	v_max3_f32 v68, v68, v79, v80
	v_add_f32_e32 v81, v88, v118
	v_add_f32_e32 v82, v89, v119
	s_waitcnt lgkmcnt(8)
	v_add_f32_e32 v120, 0, v123
	v_add_f32_e32 v121, 0, v122
	v_max3_f32 v68, v68, v81, v82
	v_add_f32_e32 v83, v90, v120
	v_add_f32_e32 v84, v91, v121
	s_waitcnt lgkmcnt(7)
	v_add_f32_e32 v122, 0, v125
	v_add_f32_e32 v123, 0, v124
	v_max3_f32 v68, v68, v83, v84
	v_add_f32_e32 v182, v94, v122
	v_add_f32_e32 v183, v95, v123
	s_waitcnt lgkmcnt(6)
	v_add_f32_e32 v124, 0, v127
	v_add_f32_e32 v125, 0, v126
	v_max3_f32 v68, v68, v182, v183
	v_add_f32_e32 v184, v96, v124
	v_add_f32_e32 v185, v97, v125
	s_waitcnt lgkmcnt(5)
	v_add_f32_e32 v126, 0, v137
	v_add_f32_e32 v127, 0, v136
	s_waitcnt lgkmcnt(3)
	v_add_f32_e32 v163, 0, v175
	v_max3_f32 v68, v68, v184, v185
	v_add_f32_e32 v186, v98, v126
	v_add_f32_e32 v187, v99, v127
	v_add_f32_e32 v136, 0, v173
	v_add_f32_e32 v137, 0, v172
	v_add_f32_e32 v175, v164, v163
	v_add_f32_e32 v164, 0, v174
	v_max3_f32 v68, v68, v186, v187
	v_add_f32_e32 v173, v100, v136
	v_add_f32_e32 v172, v101, v137
	v_add_f32_e32 v174, v165, v164
	s_waitcnt lgkmcnt(2)
	v_add_f32_e32 v165, 0, v177
	s_waitcnt lgkmcnt(1)
	v_add_f32_e32 v85, 0, v179
	v_max3_f32 v68, v68, v173, v172
	v_add_f32_e32 v177, v166, v165
	v_add_f32_e32 v166, 0, v176
	v_add_f32_e32 v168, v168, v85
	v_add_f32_e32 v85, 0, v178
	v_max3_f32 v68, v68, v175, v174
	v_add_f32_e32 v167, v167, v166
	v_add_f32_e32 v169, v169, v85
	s_waitcnt lgkmcnt(0)
	v_add_f32_e32 v85, 0, v181
	v_max3_f32 v68, v68, v177, v167
	v_add_f32_e32 v170, v170, v85
	v_add_f32_e32 v85, 0, v180
	v_max3_f32 v68, v68, v168, v169
	v_add_f32_e32 v171, v171, v85
	v_max3_f32 v68, v68, v170, v171
	ds_bpermute_b32 v85, v140, v68
	v_add_f32_e32 v36, v36, v102
	v_add_f32_e32 v37, v37, v103
	v_add_f32_e32 v38, v38, v104
	v_add_f32_e32 v39, v39, v105
	s_waitcnt lgkmcnt(0)
	v_max_f32_e32 v85, v85, v85
	v_max_f32_e32 v68, v68, v85
	ds_bpermute_b32 v85, v141, v68
	v_add_f32_e32 v40, v40, v106
	v_add_f32_e32 v41, v41, v107
	v_add_f32_e32 v42, v42, v108
	v_add_f32_e32 v43, v43, v109
	s_waitcnt lgkmcnt(0)
	v_max3_f32 v176, v68, v85, v133
	v_sub_f32_e32 v25, v25, v176
	v_exp_f32_e32 v94, v25
	v_sub_f32_e32 v24, v24, v176
	v_exp_f32_e32 v95, v24
	v_sub_f32_e32 v68, v171, v176
	v_add_f32_e32 v25, 0, v94
	v_exp_f32_e32 v68, v68
	v_add_f32_e32 v24, v95, v25
	v_sub_f32_e32 v25, v27, v176
	v_exp_f32_e32 v96, v25
	v_sub_f32_e32 v25, v26, v176
	v_exp_f32_e32 v97, v25
	v_sub_f32_e32 v25, v29, v176
	v_exp_f32_e32 v98, v25
	v_sub_f32_e32 v25, v28, v176
	v_exp_f32_e32 v99, v25
	v_sub_f32_e32 v25, v31, v176
	v_add_f32_e32 v24, v96, v24
	v_exp_f32_e32 v100, v25
	v_sub_f32_e32 v25, v30, v176
	v_add_f32_e32 v24, v97, v24
	v_exp_f32_e32 v101, v25
	v_sub_f32_e32 v25, v69, v176
	v_add_f32_e32 v24, v98, v24
	v_exp_f32_e32 v85, v25
	v_sub_f32_e32 v25, v70, v176
	v_add_f32_e32 v24, v99, v24
	v_exp_f32_e32 v86, v25
	v_sub_f32_e32 v25, v71, v176
	v_add_f32_e32 v24, v100, v24
	v_exp_f32_e32 v87, v25
	v_sub_f32_e32 v25, v72, v176
	v_add_f32_e32 v24, v101, v24
	v_exp_f32_e32 v88, v25
	v_sub_f32_e32 v25, v73, v176
	v_add_f32_e32 v24, v85, v24
	v_exp_f32_e32 v89, v25
	v_sub_f32_e32 v25, v74, v176
	v_add_f32_e32 v24, v86, v24
	v_exp_f32_e32 v90, v25
	v_sub_f32_e32 v25, v75, v176
	v_add_f32_e32 v24, v87, v24
	v_exp_f32_e32 v91, v25
	v_sub_f32_e32 v25, v76, v176
	v_add_f32_e32 v24, v88, v24
	v_exp_f32_e32 v93, v25
	v_sub_f32_e32 v25, v77, v176
	v_add_f32_e32 v24, v89, v24
	v_exp_f32_e32 v77, v25
	v_sub_f32_e32 v25, v78, v176
	v_add_f32_e32 v24, v90, v24
	v_exp_f32_e32 v78, v25
	v_sub_f32_e32 v25, v79, v176
	v_add_f32_e32 v24, v91, v24
	v_exp_f32_e32 v79, v25
	v_sub_f32_e32 v25, v80, v176
	v_add_f32_e32 v24, v93, v24
	v_exp_f32_e32 v80, v25
	v_sub_f32_e32 v25, v81, v176
	v_add_f32_e32 v24, v77, v24
	v_exp_f32_e32 v81, v25
	v_sub_f32_e32 v25, v82, v176
	v_add_f32_e32 v24, v78, v24
	v_exp_f32_e32 v82, v25
	v_sub_f32_e32 v25, v83, v176
	v_add_f32_e32 v24, v79, v24
	v_exp_f32_e32 v83, v25
	v_sub_f32_e32 v25, v84, v176
	v_add_f32_e32 v24, v80, v24
	v_exp_f32_e32 v84, v25
	v_sub_f32_e32 v25, v182, v176
	v_add_f32_e32 v24, v81, v24
	v_exp_f32_e32 v69, v25
	v_sub_f32_e32 v25, v183, v176
	v_add_f32_e32 v24, v82, v24
	v_exp_f32_e32 v70, v25
	v_sub_f32_e32 v25, v184, v176
	v_add_f32_e32 v24, v83, v24
	v_exp_f32_e32 v71, v25
	v_sub_f32_e32 v25, v185, v176
	v_add_f32_e32 v24, v84, v24
	v_exp_f32_e32 v72, v25
	v_sub_f32_e32 v25, v186, v176
	v_add_f32_e32 v24, v69, v24
	v_exp_f32_e32 v73, v25
	v_sub_f32_e32 v25, v187, v176
	v_add_f32_e32 v24, v70, v24
	v_exp_f32_e32 v74, v25
	v_sub_f32_e32 v25, v173, v176
	v_add_f32_e32 v24, v71, v24
	v_exp_f32_e32 v75, v25
	v_sub_f32_e32 v25, v172, v176
	v_add_f32_e32 v24, v72, v24
	v_exp_f32_e32 v76, v25
	v_sub_f32_e32 v25, v175, v176
	v_add_f32_e32 v24, v73, v24
	v_exp_f32_e32 v25, v25
	v_sub_f32_e32 v26, v174, v176
	v_add_f32_e32 v24, v74, v24
	v_exp_f32_e32 v26, v26
	v_sub_f32_e32 v27, v177, v176
	v_add_f32_e32 v24, v75, v24
	v_exp_f32_e32 v27, v27
	v_sub_f32_e32 v28, v167, v176
	v_add_f32_e32 v24, v76, v24
	v_exp_f32_e32 v28, v28
	v_sub_f32_e32 v29, v168, v176
	v_add_f32_e32 v24, v25, v24
	v_exp_f32_e32 v29, v29
	v_sub_f32_e32 v30, v169, v176
	v_add_f32_e32 v24, v26, v24
	v_exp_f32_e32 v30, v30
	v_sub_f32_e32 v31, v170, v176
	v_add_f32_e32 v24, v27, v24
	v_exp_f32_e32 v31, v31
	v_add_f32_e32 v24, v28, v24
	v_add_f32_e32 v24, v29, v24
	v_add_f32_e32 v24, v30, v24
	v_add_f32_e32 v24, v31, v24
	v_add_f32_e32 v24, v68, v24
	ds_bpermute_b32 v167, v140, v24
	v_add_f32_e32 v44, v44, v110
	v_add_f32_e32 v45, v45, v111
	v_add_f32_e32 v46, v46, v112
	v_add_f32_e32 v47, v47, v113
	s_waitcnt lgkmcnt(0)
	v_add_f32_e32 v24, v24, v167
	ds_bpermute_b32 v167, v141, v24
	v_add_f32_e32 v23, 0, v23
	v_add_f32_e32 v22, 0, v22
	v_add_f32_e32 v23, v48, v23
	v_add_f32_e32 v22, v49, v22
	s_waitcnt lgkmcnt(0)
	v_add_f32_e32 v24, v24, v167
	v_fma_f32 v167, v162, s6, -v176
	v_exp_f32_e32 v167, v167
	v_add_f32_e32 v21, 0, v21
	v_add_f32_e32 v20, 0, v20
	v_add_f32_e32 v21, v50, v21
	v_add_f32_e32 v24, v167, v24
	v_div_scale_f32 v167, s[0:1], v24, v24, 1.0
	v_rcp_f32_e32 v168, v167
	v_add_f32_e32 v20, v51, v20
	v_add_f32_e32 v103, v53, v115
	v_add_f32_e32 v104, v54, v116
	v_fma_f32 v169, -v167, v168, 1.0
	v_fmac_f32_e32 v168, v169, v168
	v_div_scale_f32 v169, vcc, 1.0, v24, 1.0
	v_mul_f32_e32 v170, v169, v168
	v_fma_f32 v171, -v167, v170, v169
	v_fmac_f32_e32 v170, v171, v168
	v_fma_f32 v167, -v167, v170, v169
	v_div_fmas_f32 v167, v167, v168, v170
	ds_read2_b32 v[168:169], v139 offset0:175 offset1:176
	ds_read2_b32 v[170:171], v139 offset0:173 offset1:174
	v_div_fixup_f32 v24, v167, v24, 1.0
	v_add_f32_e32 v105, v55, v117
	v_add_f32_e32 v106, v56, v118
	s_waitcnt lgkmcnt(1)
	v_add_f32_e32 v167, v92, v169
	v_add_f32_e32 v32, v32, v167
	v_add_f32_e32 v167, v92, v168
	s_waitcnt lgkmcnt(0)
	v_add_f32_e32 v168, v92, v171
	v_add_f32_e32 v33, v33, v167
	v_add_f32_e32 v34, v34, v168
	v_add_f32_e32 v168, v92, v170
	v_max3_f32 v167, v32, s7, v33
	v_add_f32_e32 v35, v35, v168
	v_max3_f32 v167, v167, v34, v35
	v_max3_f32 v102, v167, v36, v37
	v_max3_f32 v102, v102, v38, v39
	v_max3_f32 v102, v102, v40, v41
	v_max3_f32 v102, v102, v42, v43
	v_max3_f32 v102, v102, v44, v45
	v_max3_f32 v102, v102, v46, v47
	v_max3_f32 v48, v102, v23, v22
	v_max3_f32 v48, v48, v21, v20
	v_add_f32_e32 v102, v52, v114
	v_max3_f32 v48, v48, v102, v103
	v_max3_f32 v48, v48, v104, v105
	v_add_f32_e32 v107, v57, v119
	v_max3_f32 v48, v48, v106, v107
	v_add_f32_e32 v108, v58, v120
	v_add_f32_e32 v109, v59, v121
	v_max3_f32 v48, v48, v108, v109
	v_add_f32_e32 v110, v60, v122
	v_add_f32_e32 v111, v61, v123
	v_max3_f32 v48, v48, v110, v111
	v_add_f32_e32 v112, v62, v124
	v_add_f32_e32 v113, v63, v125
	v_max3_f32 v48, v48, v112, v113
	v_add_f32_e32 v114, v64, v126
	v_add_f32_e32 v65, v65, v127
	v_max3_f32 v48, v48, v114, v65
	v_add_f32_e32 v66, v66, v136
	v_add_f32_e32 v67, v67, v137
	v_max3_f32 v48, v48, v66, v67
	v_add_f32_e32 v16, v16, v163
	v_add_f32_e32 v115, v17, v164
	v_max3_f32 v17, v48, v16, v115
	v_add_f32_e32 v116, v18, v165
	v_add_f32_e32 v117, v19, v166
	v_max3_f32 v17, v17, v116, v117
	ds_bpermute_b32 v18, v140, v17
	v_cvt_pk_bf16_f32 v94, v94, v95
	v_cvt_pk_bf16_f32 v95, v96, v97
	v_cvt_pk_bf16_f32 v96, v98, v99
	v_cvt_pk_bf16_f32 v97, v100, v101
	s_waitcnt lgkmcnt(0)
	v_max_f32_e32 v18, v18, v18
	v_max_f32_e32 v17, v17, v18
	ds_bpermute_b32 v18, v141, v17
	s_waitcnt lgkmcnt(0)
	v_max3_f32 v118, v17, v18, v133
	v_sub_f32_e32 v17, v32, v118
	v_exp_f32_e32 v57, v17
	v_sub_f32_e32 v18, v33, v118
	v_exp_f32_e32 v58, v18
	v_sub_f32_e32 v18, v34, v118
	v_exp_f32_e32 v59, v18
	v_sub_f32_e32 v18, v35, v118
	v_exp_f32_e32 v60, v18
	v_sub_f32_e32 v18, v36, v118
	v_add_f32_e32 v17, 0, v57
	v_exp_f32_e32 v61, v18
	v_sub_f32_e32 v18, v37, v118
	v_add_f32_e32 v17, v58, v17
	v_exp_f32_e32 v62, v18
	v_sub_f32_e32 v18, v38, v118
	v_add_f32_e32 v17, v59, v17
	v_exp_f32_e32 v63, v18
	v_sub_f32_e32 v18, v39, v118
	v_add_f32_e32 v17, v60, v17
	v_exp_f32_e32 v64, v18
	v_sub_f32_e32 v18, v40, v118
	v_add_f32_e32 v17, v61, v17
	v_exp_f32_e32 v49, v18
	v_sub_f32_e32 v18, v41, v118
	v_add_f32_e32 v17, v62, v17
	v_exp_f32_e32 v50, v18
	v_sub_f32_e32 v18, v42, v118
	v_add_f32_e32 v17, v63, v17
	v_exp_f32_e32 v51, v18
	v_sub_f32_e32 v18, v43, v118
	v_add_f32_e32 v17, v64, v17
	v_exp_f32_e32 v52, v18
	v_sub_f32_e32 v18, v44, v118
	v_add_f32_e32 v17, v49, v17
	v_exp_f32_e32 v53, v18
	v_sub_f32_e32 v18, v45, v118
	v_add_f32_e32 v17, v50, v17
	v_exp_f32_e32 v54, v18
	v_sub_f32_e32 v18, v46, v118
	v_add_f32_e32 v17, v51, v17
	v_exp_f32_e32 v55, v18
	v_sub_f32_e32 v18, v47, v118
	v_add_f32_e32 v17, v52, v17
	v_exp_f32_e32 v56, v18
	v_sub_f32_e32 v18, v23, v118
	v_add_f32_e32 v17, v53, v17
	v_exp_f32_e32 v41, v18
	v_sub_f32_e32 v18, v22, v118
	v_add_f32_e32 v17, v54, v17
	v_exp_f32_e32 v42, v18
	v_sub_f32_e32 v18, v21, v118
	v_add_f32_e32 v17, v55, v17
	v_exp_f32_e32 v43, v18
	v_sub_f32_e32 v18, v20, v118
	v_add_f32_e32 v17, v56, v17
	v_exp_f32_e32 v44, v18
	v_sub_f32_e32 v18, v102, v118
	v_add_f32_e32 v17, v41, v17
	v_exp_f32_e32 v45, v18
	v_sub_f32_e32 v18, v103, v118
	v_add_f32_e32 v17, v42, v17
	v_exp_f32_e32 v46, v18
	v_sub_f32_e32 v18, v104, v118
	v_add_f32_e32 v17, v43, v17
	v_exp_f32_e32 v47, v18
	v_sub_f32_e32 v18, v105, v118
	v_add_f32_e32 v17, v44, v17
	v_exp_f32_e32 v48, v18
	v_sub_f32_e32 v18, v106, v118
	v_add_f32_e32 v17, v45, v17
	v_exp_f32_e32 v33, v18
	v_sub_f32_e32 v18, v107, v118
	v_add_f32_e32 v17, v46, v17
	v_exp_f32_e32 v34, v18
	v_sub_f32_e32 v18, v108, v118
	v_add_f32_e32 v17, v47, v17
	v_exp_f32_e32 v35, v18
	v_sub_f32_e32 v18, v109, v118
	v_add_f32_e32 v17, v48, v17
	v_exp_f32_e32 v36, v18
	v_sub_f32_e32 v18, v110, v118
	v_add_f32_e32 v17, v33, v17
	v_exp_f32_e32 v37, v18
	v_sub_f32_e32 v18, v111, v118
	v_add_f32_e32 v17, v34, v17
	v_exp_f32_e32 v38, v18
	v_sub_f32_e32 v18, v112, v118
	v_add_f32_e32 v17, v35, v17
	v_exp_f32_e32 v39, v18
	v_sub_f32_e32 v18, v113, v118
	v_add_f32_e32 v17, v36, v17
	v_exp_f32_e32 v40, v18
	v_add_f32_e32 v17, v37, v17
	v_add_f32_e32 v17, v38, v17
	v_add_f32_e32 v17, v39, v17
	v_add_f32_e32 v18, v40, v17
	v_sub_f32_e32 v17, v114, v118
	v_exp_f32_e32 v17, v17
	v_sub_f32_e32 v16, v16, v118
	v_sub_f32_e32 v23, v116, v118
	v_exp_f32_e32 v23, v23
	v_add_f32_e32 v19, v17, v18
	v_sub_f32_e32 v18, v65, v118
	v_exp_f32_e32 v18, v18
	v_sub_f32_e32 v32, v117, v118
	v_exp_f32_e32 v32, v32
	v_cvt_pk_bf16_f32 v58, v57, v58
	v_add_f32_e32 v20, v18, v19
	v_sub_f32_e32 v19, v66, v118
	v_exp_f32_e32 v19, v19
	v_cvt_pk_bf16_f32 v59, v59, v60
	v_cvt_pk_bf16_f32 v60, v61, v62
	v_cvt_pk_bf16_f32 v61, v63, v64
	ds_read_b128 v[110:113], v142 offset:53888
	v_add_f32_e32 v21, v19, v20
	v_sub_f32_e32 v20, v67, v118
	v_exp_f32_e32 v20, v20
	s_nop 0
	v_add_f32_e32 v22, v20, v21
	v_exp_f32_e32 v21, v16
	s_nop 0
	v_add_f32_e32 v16, v21, v22
	v_sub_f32_e32 v22, v115, v118
	v_exp_f32_e32 v22, v22
	s_nop 0
	v_add_f32_e32 v16, v22, v16
	v_add_f32_e32 v16, v23, v16
	v_add_f32_e32 v16, v32, v16
	ds_bpermute_b32 v65, v140, v16
	s_waitcnt lgkmcnt(0)
	v_add_f32_e32 v16, v16, v65
	ds_bpermute_b32 v65, v141, v16
	s_waitcnt lgkmcnt(0)
	v_add_f32_e32 v16, v16, v65
	v_fma_f32 v65, v162, s6, -v118
	v_exp_f32_e32 v65, v65
	ds_read_b128 v[118:121], v142 offset:62336
	v_mfma_f32_16x16x32_bf16 v[114:117], v[110:113], v[94:97], 0
	v_add_f32_e32 v16, v65, v16
	v_div_scale_f32 v65, s[0:1], v16, v16, 1.0
	v_rcp_f32_e32 v66, v65
	v_mfma_f32_16x16x32_bf16 v[110:113], v[110:113], v[58:61], 0
	v_fma_f32 v67, -v65, v66, 1.0
	v_fmac_f32_e32 v66, v67, v66
	v_div_scale_f32 v67, vcc, 1.0, v16, 1.0
	v_mul_f32_e32 v102, v67, v66
	v_fma_f32 v103, -v65, v102, v67
	v_fmac_f32_e32 v102, v103, v66
	v_fma_f32 v65, -v65, v102, v67
	v_div_fmas_f32 v65, v65, v66, v102
	v_div_fixup_f32 v16, v65, v16, 1.0
	ds_read_b128 v[62:65], v142 offset:36992
	ds_read_b128 v[102:105], v142 offset:45440
	v_cvt_pk_bf16_f32 v86, v85, v86
	v_cvt_pk_bf16_f32 v87, v87, v88
	v_cvt_pk_bf16_f32 v88, v89, v90
	v_cvt_pk_bf16_f32 v89, v91, v93
	v_cvt_pk_bf16_f32 v50, v49, v50
	v_cvt_pk_bf16_f32 v51, v51, v52
	v_cvt_pk_bf16_f32 v52, v53, v54
	v_cvt_pk_bf16_f32 v53, v55, v56
	ds_read_b128 v[54:57], v142 offset:37056
	s_waitcnt lgkmcnt(2)
	v_mfma_f32_16x16x32_bf16 v[98:101], v[62:65], v[94:97], 0
	v_mfma_f32_16x16x32_bf16 v[62:65], v[62:65], v[58:61], 0
	s_waitcnt lgkmcnt(0)
	v_mfma_f32_16x16x32_bf16 v[98:101], v[54:57], v[86:89], v[98:101]
	v_mfma_f32_16x16x32_bf16 v[54:57], v[54:57], v[50:53], v[62:65]
	s_nop 4
	ds_read_b128 v[62:65], v142 offset:45504
	v_mfma_f32_16x16x32_bf16 v[106:109], v[102:105], v[94:97], 0
	v_mfma_f32_16x16x32_bf16 v[102:105], v[102:105], v[58:61], 0
	s_waitcnt lgkmcnt(0)
	v_mfma_f32_16x16x32_bf16 v[106:109], v[62:65], v[86:89], v[106:109]
	v_mfma_f32_16x16x32_bf16 v[62:65], v[62:65], v[50:53], v[102:105]
	s_nop 4
	ds_read_b128 v[102:105], v142 offset:53952
	s_waitcnt lgkmcnt(0)
	v_mfma_f32_16x16x32_bf16 v[114:117], v[102:105], v[86:89], v[114:117]
	v_mfma_f32_16x16x32_bf16 v[102:105], v[102:105], v[50:53], v[110:113]
	s_nop 2
	ds_read_b128 v[110:113], v142 offset:62400
	v_mfma_f32_16x16x32_bf16 v[58:61], v[118:121], v[58:61], 0
	s_waitcnt lgkmcnt(0)
	v_mfma_f32_16x16x32_bf16 v[50:53], v[110:113], v[50:53], v[58:61]
	v_cvt_pk_bf16_f32 v58, v77, v78
	v_cvt_pk_bf16_f32 v59, v79, v80
	v_cvt_pk_bf16_f32 v60, v81, v82
	v_cvt_pk_bf16_f32 v61, v83, v84
	v_cvt_pk_bf16_f32 v42, v41, v42
	v_cvt_pk_bf16_f32 v43, v43, v44
	v_cvt_pk_bf16_f32 v44, v45, v46
	v_cvt_pk_bf16_f32 v45, v47, v48
	ds_read_b128 v[46:49], v142 offset:37120
	s_waitcnt lgkmcnt(0)
	s_nop 3
	v_mfma_f32_16x16x32_bf16 v[78:81], v[46:49], v[58:61], v[98:101]
	s_nop 2
	ds_read_b128 v[98:101], v142 offset:62464
	v_mfma_f32_16x16x32_bf16 v[46:49], v[46:49], v[42:45], v[54:57]
	s_nop 2
	ds_read_b128 v[54:57], v142 offset:45568
	s_waitcnt lgkmcnt(0)
	v_mfma_f32_16x16x32_bf16 v[82:85], v[54:57], v[58:61], v[106:109]
	v_mfma_f32_16x16x32_bf16 v[54:57], v[54:57], v[42:45], v[62:65]
	s_nop 2
	ds_read_b128 v[62:65], v142 offset:54016
	v_mfma_f32_16x16x32_bf16 v[94:97], v[118:121], v[94:97], 0
	v_mfma_f32_16x16x32_bf16 v[86:89], v[110:113], v[86:89], v[94:97]
	s_waitcnt lgkmcnt(0)
	v_mfma_f32_16x16x32_bf16 v[94:97], v[62:65], v[58:61], v[114:117]
	v_mfma_f32_16x16x32_bf16 v[62:65], v[62:65], v[42:45], v[102:105]
	v_mfma_f32_16x16x32_bf16 v[42:45], v[98:101], v[42:45], v[50:53]
	v_cvt_pk_bf16_f32 v50, v69, v70
	v_cvt_pk_bf16_f32 v51, v71, v72
	v_cvt_pk_bf16_f32 v52, v73, v74
	v_cvt_pk_bf16_f32 v53, v75, v76
	v_cvt_pk_bf16_f32 v34, v33, v34
	v_cvt_pk_bf16_f32 v35, v35, v36
	v_cvt_pk_bf16_f32 v36, v37, v38
	v_cvt_pk_bf16_f32 v37, v39, v40
	ds_read_b128 v[38:41], v142 offset:37184
	s_waitcnt lgkmcnt(0)
	v_mfma_f32_16x16x32_bf16 v[70:73], v[38:41], v[50:53], v[78:81]
	v_mfma_f32_16x16x32_bf16 v[38:41], v[38:41], v[34:37], v[46:49]
	s_nop 2
	ds_read_b128 v[46:49], v142 offset:45632
	s_waitcnt lgkmcnt(0)
	v_mfma_f32_16x16x32_bf16 v[74:77], v[46:49], v[50:53], v[82:85]
	v_mfma_f32_16x16x32_bf16 v[46:49], v[46:49], v[34:37], v[54:57]
	s_nop 2
	ds_read_b128 v[54:57], v142 offset:54080
	s_waitcnt lgkmcnt(0)
	v_mfma_f32_16x16x32_bf16 v[78:81], v[54:57], v[50:53], v[94:97]
	v_mfma_f32_16x16x32_bf16 v[54:57], v[54:57], v[34:37], v[62:65]
	s_nop 2
	ds_read_b128 v[62:65], v142 offset:62528
	v_cvt_pk_bf16_f32 v26, v25, v26
	v_cvt_pk_bf16_f32 v27, v27, v28
	v_cvt_pk_bf16_f32 v28, v29, v30
	v_cvt_pk_bf16_f32 v29, v31, v68
	v_cvt_pk_bf16_f32 v18, v17, v18
	v_cvt_pk_bf16_f32 v19, v19, v20
	v_cvt_pk_bf16_f32 v20, v21, v22
	v_cvt_pk_bf16_f32 v21, v23, v32
	ds_read_b128 v[30:33], v142 offset:37248
	s_waitcnt lgkmcnt(1)
	v_mfma_f32_16x16x32_bf16 v[34:37], v[62:65], v[34:37], v[42:45]
	v_or_b32_e32 v22, 64, v132
	v_ashrrev_i32_e32 v23, 31, v22
	v_lshlrev_b64 v[22:23], 12, v[22:23]
	s_waitcnt lgkmcnt(0)
	v_mfma_f32_16x16x32_bf16 v[42:45], v[30:33], v[26:29], v[70:73]
	v_lshl_add_u64 v[22:23], v[134:135], 0, v[22:23]
	s_nop 6
	v_mfma_f32_16x16x32_bf16 v[30:33], v[30:33], v[18:21], v[38:41]
	s_nop 1
	ds_read_b128 v[38:41], v142 offset:45696
	v_mfma_f32_16x16x32_bf16 v[58:61], v[98:101], v[58:61], v[86:89]
	v_mfma_f32_16x16x32_bf16 v[50:53], v[62:65], v[50:53], v[58:61]
	s_waitcnt lgkmcnt(0)
	v_mfma_f32_16x16x32_bf16 v[58:61], v[38:41], v[26:29], v[74:77]
	v_mfma_f32_16x16x32_bf16 v[38:41], v[38:41], v[18:21], v[46:49]
	s_nop 2
	ds_read_b128 v[46:49], v142 offset:54144
	s_waitcnt lgkmcnt(0)
	v_mfma_f32_16x16x32_bf16 v[62:65], v[46:49], v[26:29], v[78:81]
	v_mfma_f32_16x16x32_bf16 v[46:49], v[46:49], v[18:21], v[54:57]
	s_nop 2
	ds_read_b128 v[54:57], v142 offset:62592
	s_waitcnt lgkmcnt(0)
	v_mfma_f32_16x16x32_bf16 v[18:21], v[54:57], v[18:21], v[34:37]
	v_mfma_f32_16x16x32_bf16 v[26:29], v[54:57], v[26:29], v[50:53]
	v_mul_f32_e32 v42, v24, v42
	v_mul_f32_e32 v43, v24, v43
	v_mul_f32_e32 v44, v24, v44
	v_mul_f32_e32 v45, v24, v45
	v_mul_f32_e32 v58, v24, v58
	v_mul_f32_e32 v59, v24, v59
	v_mul_f32_e32 v60, v24, v60
	v_mul_f32_e32 v61, v24, v61
	v_mul_f32_e32 v62, v24, v62
	v_mul_f32_e32 v63, v24, v63
	v_mul_f32_e32 v64, v24, v64
	v_mul_f32_e32 v65, v24, v65
	v_mul_f32_e32 v26, v24, v26
	v_mul_f32_e32 v27, v24, v27
	v_mul_f32_e32 v28, v24, v28
	v_mul_f32_e32 v29, v24, v29
	v_cvt_pk_bf16_f32 v42, v42, v43
	v_cvt_pk_bf16_f32 v43, v44, v45
	v_cvt_pk_bf16_f32 v44, v58, v59
	v_cvt_pk_bf16_f32 v45, v60, v61
	v_cvt_pk_bf16_f32 v62, v62, v63
	v_cvt_pk_bf16_f32 v63, v64, v65
	v_cvt_pk_bf16_f32 v64, v26, v27
	v_cvt_pk_bf16_f32 v65, v28, v29
	s_nop 1
	v_permlane16_swap_b32_e32 v42, v44
	v_permlane16_swap_b32_e32 v43, v45
	v_permlane16_swap_b32_e32 v62, v64
	v_permlane16_swap_b32_e32 v63, v65
	global_store_dwordx4 v[22:23], v[42:45], off
	global_store_dwordx4 v[22:23], v[62:65], off offset:64
	v_or_b32_e32 v22, 0x50, v132
	v_ashrrev_i32_e32 v23, 31, v22
	v_lshlrev_b64 v[22:23], 12, v[22:23]
	v_lshl_add_u64 v[22:23], v[134:135], 0, v[22:23]
	v_mul_f32_e32 v30, v16, v30
	v_mul_f32_e32 v31, v16, v31
	v_mul_f32_e32 v32, v16, v32
	v_mul_f32_e32 v33, v16, v33
	v_mul_f32_e32 v38, v16, v38
	v_mul_f32_e32 v39, v16, v39
	v_mul_f32_e32 v40, v16, v40
	v_mul_f32_e32 v41, v16, v41
	v_mul_f32_e32 v46, v16, v46
	v_mul_f32_e32 v47, v16, v47
	v_mul_f32_e32 v48, v16, v48
	v_mul_f32_e32 v49, v16, v49
	v_mul_f32_e32 v18, v16, v18
	v_mul_f32_e32 v19, v16, v19
	v_mul_f32_e32 v20, v16, v20
	v_mul_f32_e32 v21, v16, v21
	v_cvt_pk_bf16_f32 v30, v30, v31
	v_cvt_pk_bf16_f32 v31, v32, v33
	v_cvt_pk_bf16_f32 v32, v38, v39
	v_cvt_pk_bf16_f32 v33, v40, v41
	v_cvt_pk_bf16_f32 v46, v46, v47
	v_cvt_pk_bf16_f32 v47, v48, v49
	v_cvt_pk_bf16_f32 v48, v18, v19
	v_cvt_pk_bf16_f32 v49, v20, v21
	s_nop 1
	v_permlane16_swap_b32_e32 v30, v32
	v_permlane16_swap_b32_e32 v31, v33
	v_permlane16_swap_b32_e32 v46, v48
	v_permlane16_swap_b32_e32 v47, v49
	global_store_dwordx4 v[22:23], v[30:33], off
	global_store_dwordx4 v[22:23], v[46:49], off offset:64
	ds_read_b128 v[16:19], v153 offset:13824
	ds_read_b128 v[20:23], v153 offset:13888
	s_waitcnt vmcnt(15) lgkmcnt(1)
	v_mfma_f32_16x16x32_bf16 v[24:27], v[16:19], v[4:7], 0
	s_waitcnt vmcnt(13)
	v_mfma_f32_16x16x32_bf16 v[16:19], v[16:19], v[8:11], 0
	s_waitcnt lgkmcnt(0)
	v_mfma_f32_16x16x32_bf16 v[52:55], v[20:23], v[0:3], v[24:27]
	s_waitcnt vmcnt(12)
	v_mfma_f32_16x16x32_bf16 v[16:19], v[20:23], v[12:15], v[16:19]
	ds_read_b128 v[20:23], v153 offset:16128
	s_nop 0
	ds_read_b128 v[24:27], v153 offset:16192
	s_waitcnt lgkmcnt(1)
	v_mfma_f32_16x16x32_bf16 v[28:31], v[20:23], v[4:7], 0
	v_mfma_f32_16x16x32_bf16 v[20:23], v[20:23], v[8:11], 0
	s_waitcnt lgkmcnt(0)
	v_mfma_f32_16x16x32_bf16 v[56:59], v[24:27], v[0:3], v[28:31]
	v_mfma_f32_16x16x32_bf16 v[20:23], v[24:27], v[12:15], v[20:23]
	ds_read_b128 v[24:27], v153 offset:18432
	s_nop 2
	ds_read_b128 v[28:31], v153 offset:18496
	s_waitcnt lgkmcnt(1)
	v_mfma_f32_16x16x32_bf16 v[32:35], v[24:27], v[4:7], 0
	v_mfma_f32_16x16x32_bf16 v[24:27], v[24:27], v[8:11], 0
	s_waitcnt lgkmcnt(0)
	v_mfma_f32_16x16x32_bf16 v[60:63], v[28:31], v[0:3], v[32:35]
	v_mfma_f32_16x16x32_bf16 v[24:27], v[28:31], v[12:15], v[24:27]
	ds_read_b128 v[28:31], v153 offset:20736
	s_nop 2
	ds_read_b128 v[32:35], v153 offset:20800
	s_waitcnt lgkmcnt(1)
	v_mfma_f32_16x16x32_bf16 v[36:39], v[28:31], v[4:7], 0
	v_mfma_f32_16x16x32_bf16 v[28:31], v[28:31], v[8:11], 0
	s_waitcnt lgkmcnt(0)
	v_mfma_f32_16x16x32_bf16 v[64:67], v[32:35], v[0:3], v[36:39]
	v_mfma_f32_16x16x32_bf16 v[28:31], v[32:35], v[12:15], v[28:31]
	ds_read_b128 v[32:35], v153 offset:23040
	s_nop 2
	ds_read_b128 v[36:39], v153 offset:23104
	s_waitcnt lgkmcnt(1)
	v_mfma_f32_16x16x32_bf16 v[40:43], v[32:35], v[4:7], 0
	v_mfma_f32_16x16x32_bf16 v[32:35], v[32:35], v[8:11], 0
	s_waitcnt lgkmcnt(0)
	v_mfma_f32_16x16x32_bf16 v[68:71], v[36:39], v[0:3], v[40:43]
	v_mfma_f32_16x16x32_bf16 v[32:35], v[36:39], v[12:15], v[32:35]
	ds_read_b128 v[36:39], v153 offset:25344
	s_nop 2
	ds_read_b128 v[40:43], v153 offset:25408
	s_waitcnt lgkmcnt(1)
	v_mfma_f32_16x16x32_bf16 v[44:47], v[36:39], v[4:7], 0
	v_mfma_f32_16x16x32_bf16 v[36:39], v[36:39], v[8:11], 0
	s_waitcnt lgkmcnt(0)
	v_mfma_f32_16x16x32_bf16 v[72:75], v[40:43], v[0:3], v[44:47]
	v_mfma_f32_16x16x32_bf16 v[36:39], v[40:43], v[12:15], v[36:39]
	ds_read_b128 v[40:43], v153 offset:27648
	s_nop 2
	ds_read_b128 v[44:47], v153 offset:27712
	s_waitcnt lgkmcnt(1)
	v_mfma_f32_16x16x32_bf16 v[48:51], v[40:43], v[4:7], 0
	v_mfma_f32_16x16x32_bf16 v[40:43], v[40:43], v[8:11], 0
	s_waitcnt lgkmcnt(0)
	v_mfma_f32_16x16x32_bf16 v[76:79], v[44:47], v[0:3], v[48:51]
	v_mfma_f32_16x16x32_bf16 v[40:43], v[44:47], v[12:15], v[40:43]
	ds_read_b128 v[44:47], v153 offset:29952
	s_nop 2
	ds_read_b128 v[48:51], v153 offset:30016
	s_waitcnt lgkmcnt(1)
	v_mfma_f32_16x16x32_bf16 v[80:83], v[44:47], v[4:7], 0
	v_mfma_f32_16x16x32_bf16 v[44:47], v[44:47], v[8:11], 0
	s_waitcnt lgkmcnt(0)
	v_mfma_f32_16x16x32_bf16 v[80:83], v[48:51], v[0:3], v[80:83]
	v_mfma_f32_16x16x32_bf16 v[44:47], v[48:51], v[12:15], v[44:47]
	ds_read_b128 v[48:51], v153 offset:32256
	ds_read_b128 v[84:87], v153 offset:32320
	s_waitcnt lgkmcnt(1)
	v_mfma_f32_16x16x32_bf16 v[88:91], v[48:51], v[4:7], 0
	v_mfma_f32_16x16x32_bf16 v[48:51], v[48:51], v[8:11], 0
	s_waitcnt lgkmcnt(0)
	v_mfma_f32_16x16x32_bf16 v[116:119], v[84:87], v[0:3], v[88:91]
	v_mfma_f32_16x16x32_bf16 v[48:51], v[84:87], v[12:15], v[48:51]
	ds_read_b128 v[84:87], v153 offset:34560
	s_nop 2
	ds_read_b128 v[88:91], v153 offset:34624
	s_waitcnt lgkmcnt(1)
	v_mfma_f32_16x16x32_bf16 v[4:7], v[84:87], v[4:7], 0
	s_waitcnt lgkmcnt(0)
	v_mfma_f32_16x16x32_bf16 v[120:123], v[88:91], v[0:3], v[4:7]
	v_mfma_f32_16x16x32_bf16 v[0:3], v[84:87], v[8:11], 0
	v_mfma_f32_16x16x32_bf16 v[0:3], v[88:91], v[12:15], v[0:3]
	ds_read2_b32 v[8:9], v139 offset0:159 offset1:160
	ds_read2_b32 v[10:11], v139 offset0:157 offset1:158
	s_nop 1
	ds_read2_b32 v[6:7], v139 offset0:143 offset1:144
	ds_read2_b32 v[4:5], v139 offset0:141 offset1:142
	ds_read2_b32 v[12:13], v139 offset0:127 offset1:128
	ds_read2_b32 v[14:15], v139 offset0:125 offset1:126
	ds_read2_b32 v[96:97], v139 offset0:111 offset1:112
	ds_read2_b32 v[98:99], v139 offset0:109 offset1:110
	ds_read2_b32 v[100:101], v139 offset0:95 offset1:96
	ds_read2_b32 v[102:103], v139 offset0:93 offset1:94
	ds_read2_b32 v[104:105], v139 offset0:79 offset1:80
	ds_read2_b32 v[106:107], v139 offset0:77 offset1:78
	ds_read2_b32 v[108:109], v139 offset0:63 offset1:64
	ds_read2_b32 v[110:111], v139 offset0:61 offset1:62
	ds_read2_b32 v[112:113], v139 offset0:47 offset1:48
	ds_read2_b32 v[114:115], v139 offset0:45 offset1:46
	ds_read2_b32 v[124:125], v139 offset0:31 offset1:32
	ds_read2_b32 v[126:127], v139 offset0:29 offset1:30
	ds_read2_b32 v[136:137], v139 offset0:15 offset1:16
	ds_read2_b32 v[164:165], v139 offset0:13 offset1:14
	s_waitcnt lgkmcnt(14)
	v_add_f32_e32 v85, v92, v9
	v_add_f32_e32 v86, v92, v8
	v_add_f32_e32 v9, v52, v85
	v_add_f32_e32 v8, v53, v86
	v_add_f32_e32 v87, v92, v11
	v_add_f32_e32 v88, v92, v10
	v_max3_f32 v52, v9, s7, v8
	v_add_f32_e32 v11, v54, v87
	v_add_f32_e32 v10, v55, v88
	v_add_f32_e32 v53, v92, v7
	v_add_f32_e32 v54, v92, v6
	v_max3_f32 v52, v52, v11, v10
	v_add_f32_e32 v53, v56, v53
	v_add_f32_e32 v54, v57, v54
	v_add_f32_e32 v55, v92, v5
	v_add_f32_e32 v56, v92, v4
	v_max3_f32 v52, v52, v53, v54
	v_add_f32_e32 v55, v58, v55
	v_add_f32_e32 v56, v59, v56
	v_add_f32_e32 v89, 0, v13
	v_add_f32_e32 v90, 0, v12
	v_max3_f32 v52, v52, v55, v56
	v_add_f32_e32 v13, v60, v89
	v_add_f32_e32 v12, v61, v90
	v_add_f32_e32 v91, 0, v15
	v_add_f32_e32 v93, 0, v14
	v_max3_f32 v52, v52, v13, v12
	v_add_f32_e32 v15, v62, v91
	v_add_f32_e32 v14, v63, v93
	s_waitcnt lgkmcnt(13)
	v_add_f32_e32 v94, 0, v97
	v_add_f32_e32 v95, 0, v96
	v_max3_f32 v52, v52, v15, v14
	v_add_f32_e32 v57, v64, v94
	v_add_f32_e32 v58, v65, v95
	s_waitcnt lgkmcnt(12)
	v_add_f32_e32 v96, 0, v99
	v_add_f32_e32 v97, 0, v98
	v_max3_f32 v52, v52, v57, v58
	v_add_f32_e32 v59, v66, v96
	v_add_f32_e32 v60, v67, v97
	s_waitcnt lgkmcnt(11)
	v_add_f32_e32 v98, 0, v101
	v_add_f32_e32 v99, 0, v100
	v_max3_f32 v52, v52, v59, v60
	v_add_f32_e32 v61, v68, v98
	v_add_f32_e32 v62, v69, v99
	s_waitcnt lgkmcnt(10)
	v_add_f32_e32 v100, 0, v103
	v_add_f32_e32 v101, 0, v102
	v_max3_f32 v52, v52, v61, v62
	v_add_f32_e32 v63, v70, v100
	v_add_f32_e32 v64, v71, v101
	s_waitcnt lgkmcnt(9)
	v_add_f32_e32 v102, 0, v105
	v_add_f32_e32 v103, 0, v104
	v_max3_f32 v52, v52, v63, v64
	v_add_f32_e32 v65, v72, v102
	v_add_f32_e32 v66, v73, v103
	s_waitcnt lgkmcnt(8)
	v_add_f32_e32 v104, 0, v107
	v_add_f32_e32 v105, 0, v106
	v_max3_f32 v52, v52, v65, v66
	v_add_f32_e32 v67, v74, v104
	v_add_f32_e32 v68, v75, v105
	s_waitcnt lgkmcnt(7)
	v_add_f32_e32 v106, 0, v109
	v_add_f32_e32 v107, 0, v108
	v_max3_f32 v52, v52, v67, v68
	v_add_f32_e32 v163, v76, v106
	v_add_f32_e32 v166, v77, v107
	s_waitcnt lgkmcnt(6)
	v_add_f32_e32 v108, 0, v111
	v_add_f32_e32 v109, 0, v110
	v_max3_f32 v52, v52, v163, v166
	v_add_f32_e32 v167, v78, v108
	v_add_f32_e32 v168, v79, v109
	s_waitcnt lgkmcnt(5)
	v_add_f32_e32 v110, 0, v113
	v_add_f32_e32 v111, 0, v112
	v_max3_f32 v52, v52, v167, v168
	v_add_f32_e32 v169, v80, v110
	v_add_f32_e32 v170, v81, v111
	s_waitcnt lgkmcnt(4)
	v_add_f32_e32 v112, 0, v115
	v_add_f32_e32 v113, 0, v114
	v_max3_f32 v52, v52, v169, v170
	v_add_f32_e32 v171, v82, v112
	v_add_f32_e32 v172, v83, v113
	s_waitcnt lgkmcnt(3)
	v_add_f32_e32 v114, 0, v125
	v_add_f32_e32 v115, 0, v124
	s_waitcnt lgkmcnt(1)
	v_add_f32_e32 v69, 0, v137
	v_max3_f32 v52, v52, v171, v172
	v_add_f32_e32 v125, v116, v114
	v_add_f32_e32 v124, v117, v115
	v_add_f32_e32 v116, 0, v127
	v_add_f32_e32 v117, 0, v126
	v_add_f32_e32 v120, v120, v69
	v_add_f32_e32 v69, 0, v136
	v_max3_f32 v52, v52, v125, v124
	v_add_f32_e32 v118, v118, v116
	v_add_f32_e32 v119, v119, v117
	v_add_f32_e32 v121, v121, v69
	s_waitcnt lgkmcnt(0)
	v_add_f32_e32 v69, 0, v165
	v_max3_f32 v52, v52, v118, v119
	v_add_f32_e32 v122, v122, v69
	v_add_f32_e32 v69, 0, v164
	v_max3_f32 v52, v52, v120, v121
	v_add_f32_e32 v123, v123, v69
	v_max3_f32 v52, v52, v122, v123
	ds_bpermute_b32 v69, v140, v52
	v_add_f32_e32 v20, v20, v85
	v_add_f32_e32 v21, v21, v86
	v_add_f32_e32 v22, v22, v87
	v_add_f32_e32 v23, v23, v88
	s_waitcnt lgkmcnt(0)
	v_max_f32_e32 v69, v69, v69
	v_max_f32_e32 v52, v52, v69
	ds_bpermute_b32 v69, v141, v52
	v_add_f32_e32 v7, 0, v7
	v_add_f32_e32 v6, 0, v6
	v_add_f32_e32 v7, v24, v7
	v_add_f32_e32 v6, v25, v6
	s_waitcnt lgkmcnt(0)
	v_max3_f32 v126, v52, v69, v133
	v_sub_f32_e32 v9, v9, v126
	v_exp_f32_e32 v77, v9
	v_sub_f32_e32 v8, v8, v126
	v_exp_f32_e32 v78, v8
	v_sub_f32_e32 v52, v123, v126
	v_add_f32_e32 v9, 0, v77
	v_exp_f32_e32 v52, v52
	v_add_f32_e32 v8, v78, v9
	v_sub_f32_e32 v9, v11, v126
	v_exp_f32_e32 v79, v9
	v_sub_f32_e32 v9, v10, v126
	v_exp_f32_e32 v80, v9
	v_sub_f32_e32 v9, v53, v126
	v_exp_f32_e32 v81, v9
	v_sub_f32_e32 v9, v54, v126
	v_exp_f32_e32 v82, v9
	v_sub_f32_e32 v9, v55, v126
	v_add_f32_e32 v8, v79, v8
	v_exp_f32_e32 v83, v9
	v_sub_f32_e32 v9, v56, v126
	v_add_f32_e32 v8, v80, v8
	v_exp_f32_e32 v84, v9
	v_sub_f32_e32 v9, v13, v126
	v_add_f32_e32 v8, v81, v8
	v_exp_f32_e32 v69, v9
	v_sub_f32_e32 v9, v12, v126
	v_add_f32_e32 v8, v82, v8
	v_exp_f32_e32 v70, v9
	v_sub_f32_e32 v9, v15, v126
	v_add_f32_e32 v8, v83, v8
	v_exp_f32_e32 v71, v9
	v_sub_f32_e32 v9, v14, v126
	v_add_f32_e32 v8, v84, v8
	v_exp_f32_e32 v72, v9
	v_sub_f32_e32 v9, v57, v126
	v_add_f32_e32 v8, v69, v8
	v_exp_f32_e32 v73, v9
	v_sub_f32_e32 v9, v58, v126
	v_add_f32_e32 v8, v70, v8
	v_exp_f32_e32 v74, v9
	v_sub_f32_e32 v9, v59, v126
	v_add_f32_e32 v8, v71, v8
	v_exp_f32_e32 v75, v9
	v_sub_f32_e32 v9, v60, v126
	v_add_f32_e32 v8, v72, v8
	v_exp_f32_e32 v76, v9
	v_sub_f32_e32 v9, v61, v126
	v_add_f32_e32 v8, v73, v8
	v_exp_f32_e32 v61, v9
	v_sub_f32_e32 v9, v62, v126
	v_add_f32_e32 v8, v74, v8
	v_exp_f32_e32 v62, v9
	v_sub_f32_e32 v9, v63, v126
	v_add_f32_e32 v8, v75, v8
	v_exp_f32_e32 v63, v9
	v_sub_f32_e32 v9, v64, v126
	v_add_f32_e32 v8, v76, v8
	v_exp_f32_e32 v64, v9
	v_sub_f32_e32 v9, v65, v126
	v_add_f32_e32 v8, v61, v8
	v_exp_f32_e32 v65, v9
	v_sub_f32_e32 v9, v66, v126
	v_add_f32_e32 v8, v62, v8
	v_exp_f32_e32 v66, v9
	v_sub_f32_e32 v9, v67, v126
	v_add_f32_e32 v8, v63, v8
	v_exp_f32_e32 v67, v9
	v_sub_f32_e32 v9, v68, v126
	v_add_f32_e32 v8, v64, v8
	v_exp_f32_e32 v68, v9
	v_sub_f32_e32 v9, v163, v126
	v_add_f32_e32 v8, v65, v8
	v_exp_f32_e32 v53, v9
	v_sub_f32_e32 v9, v166, v126
	v_add_f32_e32 v8, v66, v8
	v_exp_f32_e32 v54, v9
	v_sub_f32_e32 v9, v167, v126
	v_add_f32_e32 v8, v67, v8
	v_exp_f32_e32 v55, v9
	v_sub_f32_e32 v9, v168, v126
	v_add_f32_e32 v8, v68, v8
	v_exp_f32_e32 v56, v9
	v_sub_f32_e32 v9, v169, v126
	v_add_f32_e32 v8, v53, v8
	v_exp_f32_e32 v57, v9
	v_sub_f32_e32 v9, v170, v126
	v_add_f32_e32 v8, v54, v8
	v_exp_f32_e32 v58, v9
	v_sub_f32_e32 v9, v171, v126
	v_add_f32_e32 v8, v55, v8
	v_exp_f32_e32 v59, v9
	v_sub_f32_e32 v9, v172, v126
	v_add_f32_e32 v8, v56, v8
	v_exp_f32_e32 v60, v9
	v_sub_f32_e32 v9, v125, v126
	v_add_f32_e32 v8, v57, v8
	v_exp_f32_e32 v9, v9
	v_sub_f32_e32 v10, v124, v126
	v_add_f32_e32 v8, v58, v8
	v_exp_f32_e32 v10, v10
	v_sub_f32_e32 v11, v118, v126
	v_add_f32_e32 v8, v59, v8
	v_exp_f32_e32 v11, v11
	v_sub_f32_e32 v12, v119, v126
	v_add_f32_e32 v8, v60, v8
	v_exp_f32_e32 v12, v12
	v_sub_f32_e32 v13, v120, v126
	v_add_f32_e32 v8, v9, v8
	v_exp_f32_e32 v13, v13
	v_sub_f32_e32 v14, v121, v126
	v_add_f32_e32 v8, v10, v8
	v_exp_f32_e32 v14, v14
	v_sub_f32_e32 v15, v122, v126
	v_add_f32_e32 v8, v11, v8
	v_exp_f32_e32 v15, v15
	v_add_f32_e32 v8, v12, v8
	v_add_f32_e32 v8, v13, v8
	v_add_f32_e32 v8, v14, v8
	v_add_f32_e32 v8, v15, v8
	v_add_f32_e32 v8, v52, v8
	ds_bpermute_b32 v118, v140, v8
	v_add_f32_e32 v5, 0, v5
	v_add_f32_e32 v4, 0, v4
	v_add_f32_e32 v5, v26, v5
	v_add_f32_e32 v4, v27, v4
	s_waitcnt lgkmcnt(0)
	v_add_f32_e32 v8, v8, v118
	ds_bpermute_b32 v118, v141, v8
	v_add_f32_e32 v25, v28, v89
	v_add_f32_e32 v26, v29, v90
	v_add_f32_e32 v27, v30, v91
	v_add_f32_e32 v28, v31, v93
	s_waitcnt lgkmcnt(0)
	v_add_f32_e32 v8, v8, v118
	v_fma_f32 v118, v162, s6, -v126
	v_exp_f32_e32 v118, v118
	v_add_f32_e32 v29, v32, v94
	v_add_f32_e32 v30, v33, v95
	v_add_f32_e32 v31, v34, v96
	v_add_f32_e32 v8, v118, v8
	v_div_scale_f32 v118, s[0:1], v8, v8, 1.0
	v_rcp_f32_e32 v119, v118
	v_add_f32_e32 v32, v35, v97
	v_add_f32_e32 v86, v37, v99
	v_add_f32_e32 v87, v38, v100
	v_fma_f32 v120, -v118, v119, 1.0
	v_fmac_f32_e32 v119, v120, v119
	v_div_scale_f32 v120, vcc, 1.0, v8, 1.0
	v_mul_f32_e32 v121, v120, v119
	v_fma_f32 v122, -v118, v121, v120
	v_fmac_f32_e32 v121, v122, v119
	v_fma_f32 v118, -v118, v121, v120
	v_div_fmas_f32 v118, v118, v119, v121
	v_div_fixup_f32 v8, v118, v8, 1.0
	ds_read2_b32 v[118:119], v139 offset0:175 offset1:176
	ds_read2_b32 v[120:121], v139 offset0:173 offset1:174
	v_add_f32_e32 v88, v39, v101
	v_add_f32_e32 v89, v40, v102
	v_add_f32_e32 v90, v41, v103
	s_waitcnt lgkmcnt(1)
	v_add_f32_e32 v119, v92, v119
	v_add_f32_e32 v118, v92, v118
	v_add_f32_e32 v16, v16, v119
	v_add_f32_e32 v17, v17, v118
	s_waitcnt lgkmcnt(0)
	v_add_f32_e32 v119, v92, v121
	v_add_f32_e32 v92, v92, v120
	v_max3_f32 v118, v16, s7, v17
	v_add_f32_e32 v18, v18, v119
	v_add_f32_e32 v19, v19, v92
	v_max3_f32 v92, v118, v18, v19
	v_max3_f32 v85, v92, v20, v21
	v_max3_f32 v85, v85, v22, v23
	v_max3_f32 v24, v85, v7, v6
	v_max3_f32 v24, v24, v5, v4
	v_max3_f32 v24, v24, v25, v26
	v_max3_f32 v24, v24, v27, v28
	v_max3_f32 v24, v24, v29, v30
	v_max3_f32 v24, v24, v31, v32
	v_add_f32_e32 v85, v36, v98
	v_max3_f32 v24, v24, v85, v86
	v_max3_f32 v24, v24, v87, v88
	v_max3_f32 v24, v24, v89, v90
	v_add_f32_e32 v91, v42, v104
	v_add_f32_e32 v92, v43, v105
	v_max3_f32 v24, v24, v91, v92
	v_add_f32_e32 v93, v44, v106
	v_add_f32_e32 v94, v45, v107
	v_max3_f32 v24, v24, v93, v94
	v_add_f32_e32 v95, v46, v108
	v_add_f32_e32 v96, v47, v109
	v_max3_f32 v24, v24, v95, v96
	v_add_f32_e32 v97, v48, v110
	v_add_f32_e32 v49, v49, v111
	v_max3_f32 v24, v24, v97, v49
	v_add_f32_e32 v50, v50, v112
	v_add_f32_e32 v51, v51, v113
	v_max3_f32 v24, v24, v50, v51
	v_add_f32_e32 v0, v0, v114
	v_add_f32_e32 v98, v1, v115
	v_max3_f32 v1, v24, v0, v98
	v_add_f32_e32 v99, v2, v116
	v_add_f32_e32 v100, v3, v117
	v_max3_f32 v1, v1, v99, v100
	ds_bpermute_b32 v2, v140, v1
	v_cvt_pk_bf16_f32 v78, v77, v78
	v_cvt_pk_bf16_f32 v79, v79, v80
	v_cvt_pk_bf16_f32 v80, v81, v82
	v_cvt_pk_bf16_f32 v81, v83, v84
	s_waitcnt lgkmcnt(0)
	v_max_f32_e32 v2, v2, v2
	v_max_f32_e32 v1, v1, v2
	ds_bpermute_b32 v2, v141, v1
	s_waitcnt lgkmcnt(0)
	v_max3_f32 v101, v1, v2, v133
	v_sub_f32_e32 v1, v16, v101
	v_exp_f32_e32 v41, v1
	v_sub_f32_e32 v2, v17, v101
	v_exp_f32_e32 v42, v2
	v_sub_f32_e32 v2, v18, v101
	v_exp_f32_e32 v43, v2
	v_sub_f32_e32 v2, v19, v101
	v_exp_f32_e32 v44, v2
	v_sub_f32_e32 v2, v20, v101
	v_add_f32_e32 v1, 0, v41
	v_exp_f32_e32 v45, v2
	v_sub_f32_e32 v2, v21, v101
	v_add_f32_e32 v1, v42, v1
	v_exp_f32_e32 v46, v2
	v_sub_f32_e32 v2, v22, v101
	v_add_f32_e32 v1, v43, v1
	v_exp_f32_e32 v47, v2
	v_sub_f32_e32 v2, v23, v101
	v_add_f32_e32 v1, v44, v1
	v_exp_f32_e32 v48, v2
	v_sub_f32_e32 v2, v7, v101
	v_add_f32_e32 v1, v45, v1
	v_exp_f32_e32 v33, v2
	v_sub_f32_e32 v2, v6, v101
	v_add_f32_e32 v1, v46, v1
	v_exp_f32_e32 v34, v2
	v_sub_f32_e32 v2, v5, v101
	v_add_f32_e32 v1, v47, v1
	v_exp_f32_e32 v35, v2
	v_sub_f32_e32 v2, v4, v101
	v_add_f32_e32 v1, v48, v1
	v_exp_f32_e32 v36, v2
	v_sub_f32_e32 v2, v25, v101
	v_add_f32_e32 v1, v33, v1
	v_exp_f32_e32 v37, v2
	v_sub_f32_e32 v2, v26, v101
	v_add_f32_e32 v1, v34, v1
	v_exp_f32_e32 v38, v2
	v_sub_f32_e32 v2, v27, v101
	v_add_f32_e32 v1, v35, v1
	v_exp_f32_e32 v39, v2
	v_sub_f32_e32 v2, v28, v101
	v_add_f32_e32 v1, v36, v1
	v_exp_f32_e32 v40, v2
	v_sub_f32_e32 v2, v29, v101
	v_add_f32_e32 v1, v37, v1
	v_exp_f32_e32 v25, v2
	v_sub_f32_e32 v2, v30, v101
	v_add_f32_e32 v1, v38, v1
	v_exp_f32_e32 v26, v2
	v_sub_f32_e32 v2, v31, v101
	v_add_f32_e32 v1, v39, v1
	v_exp_f32_e32 v27, v2
	v_sub_f32_e32 v2, v32, v101
	v_add_f32_e32 v1, v40, v1
	v_exp_f32_e32 v28, v2
	v_sub_f32_e32 v2, v85, v101
	v_add_f32_e32 v1, v25, v1
	v_exp_f32_e32 v29, v2
	v_sub_f32_e32 v2, v86, v101
	v_add_f32_e32 v1, v26, v1
	v_exp_f32_e32 v30, v2
	v_sub_f32_e32 v2, v87, v101
	v_add_f32_e32 v1, v27, v1
	v_exp_f32_e32 v31, v2
	v_sub_f32_e32 v2, v88, v101
	v_add_f32_e32 v1, v28, v1
	v_exp_f32_e32 v32, v2
	v_sub_f32_e32 v2, v89, v101
	v_add_f32_e32 v1, v29, v1
	v_exp_f32_e32 v17, v2
	v_sub_f32_e32 v2, v90, v101
	v_add_f32_e32 v1, v30, v1
	v_exp_f32_e32 v18, v2
	v_sub_f32_e32 v2, v91, v101
	v_add_f32_e32 v1, v31, v1
	v_exp_f32_e32 v19, v2
	v_sub_f32_e32 v2, v92, v101
	v_add_f32_e32 v1, v32, v1
	v_exp_f32_e32 v20, v2
	v_sub_f32_e32 v2, v93, v101
	v_add_f32_e32 v1, v17, v1
	v_exp_f32_e32 v21, v2
	v_sub_f32_e32 v2, v94, v101
	v_add_f32_e32 v1, v18, v1
	v_exp_f32_e32 v22, v2
	v_sub_f32_e32 v2, v95, v101
	v_add_f32_e32 v1, v19, v1
	v_exp_f32_e32 v23, v2
	v_sub_f32_e32 v2, v96, v101
	v_add_f32_e32 v1, v20, v1
	v_exp_f32_e32 v24, v2
	v_add_f32_e32 v1, v21, v1
	v_add_f32_e32 v1, v22, v1
	v_add_f32_e32 v1, v23, v1
	v_add_f32_e32 v2, v24, v1
	v_sub_f32_e32 v1, v97, v101
	v_exp_f32_e32 v1, v1
	v_sub_f32_e32 v0, v0, v101
	v_sub_f32_e32 v7, v99, v101
	v_exp_f32_e32 v7, v7
	v_add_f32_e32 v3, v1, v2
	v_sub_f32_e32 v2, v49, v101
	v_exp_f32_e32 v2, v2
	v_sub_f32_e32 v16, v100, v101
	v_exp_f32_e32 v16, v16
	v_cvt_pk_bf16_f32 v42, v41, v42
	v_add_f32_e32 v4, v2, v3
	v_sub_f32_e32 v3, v50, v101
	v_exp_f32_e32 v3, v3
	v_cvt_pk_bf16_f32 v43, v43, v44
	v_cvt_pk_bf16_f32 v44, v45, v46
	v_cvt_pk_bf16_f32 v45, v47, v48
	ds_read_b128 v[94:97], v142 offset:53952
	ds_read_b128 v[102:105], v142 offset:62400
	v_add_f32_e32 v5, v3, v4
	v_sub_f32_e32 v4, v51, v101
	v_exp_f32_e32 v4, v4
	s_nop 0
	v_add_f32_e32 v6, v4, v5
	v_exp_f32_e32 v5, v0
	s_nop 0
	v_add_f32_e32 v0, v5, v6
	v_sub_f32_e32 v6, v98, v101
	v_exp_f32_e32 v6, v6
	s_nop 0
	v_add_f32_e32 v0, v6, v0
	v_add_f32_e32 v0, v7, v0
	v_add_f32_e32 v0, v16, v0
	ds_bpermute_b32 v49, v140, v0
	s_waitcnt lgkmcnt(0)
	v_add_f32_e32 v0, v0, v49
	ds_bpermute_b32 v49, v141, v0
	s_waitcnt lgkmcnt(0)
	v_add_f32_e32 v0, v0, v49
	v_fma_f32 v49, v162, s6, -v101
	v_exp_f32_e32 v49, v49
	v_mfma_f32_16x16x32_bf16 v[98:101], v[94:97], v[78:81], 0
	v_add_f32_e32 v0, v49, v0
	v_div_scale_f32 v49, s[0:1], v0, v0, 1.0
	v_rcp_f32_e32 v50, v49
	v_mfma_f32_16x16x32_bf16 v[94:97], v[94:97], v[42:45], 0
	v_readlane_b32 s0, v254, 34
	s_add_i32 s29, s29, s0
	v_fma_f32 v51, -v49, v50, 1.0
	v_fmac_f32_e32 v50, v51, v50
	v_div_scale_f32 v51, vcc, 1.0, v0, 1.0
	v_mul_f32_e32 v85, v51, v50
	v_fma_f32 v86, -v49, v85, v51
	v_fmac_f32_e32 v85, v86, v50
	v_fma_f32 v49, -v49, v85, v51
	v_div_fmas_f32 v49, v49, v50, v85
	v_div_fixup_f32 v0, v49, v0, 1.0
	ds_read_b128 v[46:49], v142 offset:37056
	ds_read_b128 v[86:89], v142 offset:45504
	v_cvt_pk_bf16_f32 v70, v69, v70
	v_cvt_pk_bf16_f32 v71, v71, v72
	v_cvt_pk_bf16_f32 v72, v73, v74
	v_cvt_pk_bf16_f32 v73, v75, v76
	v_cvt_pk_bf16_f32 v34, v33, v34
	v_cvt_pk_bf16_f32 v35, v35, v36
	v_cvt_pk_bf16_f32 v36, v37, v38
	v_cvt_pk_bf16_f32 v37, v39, v40
	ds_read_b128 v[38:41], v142 offset:37120
	s_waitcnt lgkmcnt(2)
	v_mfma_f32_16x16x32_bf16 v[82:85], v[46:49], v[78:81], 0
	s_cmpk_lt_i32 s29, 0x100
	s_cselect_b64 s[0:1], -1, 0
	s_cmp_lt_u32 s11, 0x3fffffff
	v_mfma_f32_16x16x32_bf16 v[46:49], v[46:49], v[42:45], 0
	s_cselect_b64 s[6:7], -1, 0
	s_and_b64 s[0:1], s[36:37], s[0:1]
	s_and_b64 s[0:1], s[0:1], s[6:7]
	s_waitcnt lgkmcnt(0)
	v_mfma_f32_16x16x32_bf16 v[74:77], v[38:41], v[70:73], v[82:85]
	v_readlane_b32 s6, v254, 31
	s_add_i32 s28, s28, s6
	s_andn2_b64 vcc, exec, s[0:1]
	v_mfma_f32_16x16x32_bf16 v[38:41], v[38:41], v[34:37], v[46:49]
	s_mov_b32 s11, s20
	s_nop 1
	ds_read_b128 v[46:49], v142 offset:45568
	v_mfma_f32_16x16x32_bf16 v[90:93], v[86:89], v[78:81], 0
	v_mfma_f32_16x16x32_bf16 v[86:89], v[86:89], v[42:45], 0
	s_waitcnt lgkmcnt(0)
	v_mfma_f32_16x16x32_bf16 v[82:85], v[46:49], v[70:73], v[90:93]
	v_mfma_f32_16x16x32_bf16 v[46:49], v[46:49], v[34:37], v[86:89]
	s_nop 4
	ds_read_b128 v[86:89], v142 offset:54016
	s_waitcnt lgkmcnt(0)
	v_mfma_f32_16x16x32_bf16 v[90:93], v[86:89], v[70:73], v[98:101]
	v_mfma_f32_16x16x32_bf16 v[86:89], v[86:89], v[34:37], v[94:97]
	s_nop 2
	ds_read_b128 v[94:97], v142 offset:62464
	v_mfma_f32_16x16x32_bf16 v[42:45], v[102:105], v[42:45], 0
	s_waitcnt lgkmcnt(0)
	v_mfma_f32_16x16x32_bf16 v[34:37], v[94:97], v[34:37], v[42:45]
	v_cvt_pk_bf16_f32 v42, v61, v62
	v_cvt_pk_bf16_f32 v43, v63, v64
	v_cvt_pk_bf16_f32 v44, v65, v66
	v_cvt_pk_bf16_f32 v45, v67, v68
	v_cvt_pk_bf16_f32 v26, v25, v26
	v_cvt_pk_bf16_f32 v27, v27, v28
	v_cvt_pk_bf16_f32 v28, v29, v30
	v_cvt_pk_bf16_f32 v29, v31, v32
	ds_read_b128 v[30:33], v142 offset:37184
	v_mfma_f32_16x16x32_bf16 v[78:81], v[102:105], v[78:81], 0
	v_mfma_f32_16x16x32_bf16 v[70:73], v[94:97], v[70:73], v[78:81]
	s_nop 6
	ds_read_b128 v[78:81], v142 offset:62528
	s_waitcnt lgkmcnt(1)
	v_mfma_f32_16x16x32_bf16 v[62:65], v[30:33], v[42:45], v[74:77]
	v_mfma_f32_16x16x32_bf16 v[30:33], v[30:33], v[26:29], v[38:41]
	s_nop 2
	ds_read_b128 v[38:41], v142 offset:45632
	s_waitcnt lgkmcnt(0)
	v_mfma_f32_16x16x32_bf16 v[66:69], v[38:41], v[42:45], v[82:85]
	v_mfma_f32_16x16x32_bf16 v[38:41], v[38:41], v[26:29], v[46:49]
	s_nop 2
	ds_read_b128 v[46:49], v142 offset:54080
	s_waitcnt lgkmcnt(0)
	v_mfma_f32_16x16x32_bf16 v[74:77], v[46:49], v[42:45], v[90:93]
	v_mfma_f32_16x16x32_bf16 v[46:49], v[46:49], v[26:29], v[86:89]
	v_mfma_f32_16x16x32_bf16 v[26:29], v[78:81], v[26:29], v[34:37]
	v_cvt_pk_bf16_f32 v34, v53, v54
	v_cvt_pk_bf16_f32 v35, v55, v56
	v_cvt_pk_bf16_f32 v36, v57, v58
	v_cvt_pk_bf16_f32 v37, v59, v60
	v_cvt_pk_bf16_f32 v18, v17, v18
	v_cvt_pk_bf16_f32 v19, v19, v20
	v_cvt_pk_bf16_f32 v20, v21, v22
	v_cvt_pk_bf16_f32 v21, v23, v24
	ds_read_b128 v[22:25], v142 offset:37248
	s_waitcnt lgkmcnt(0)
	v_mfma_f32_16x16x32_bf16 v[54:57], v[22:25], v[34:37], v[62:65]
	v_mfma_f32_16x16x32_bf16 v[22:25], v[22:25], v[18:21], v[30:33]
	s_nop 2
	ds_read_b128 v[30:33], v142 offset:45696
	s_waitcnt lgkmcnt(0)
	v_mfma_f32_16x16x32_bf16 v[58:61], v[30:33], v[34:37], v[66:69]
	v_mfma_f32_16x16x32_bf16 v[30:33], v[30:33], v[18:21], v[38:41]
	s_nop 2
	ds_read_b128 v[38:41], v142 offset:54144
	s_waitcnt lgkmcnt(0)
	v_mfma_f32_16x16x32_bf16 v[62:65], v[38:41], v[34:37], v[74:77]
	v_mfma_f32_16x16x32_bf16 v[38:41], v[38:41], v[18:21], v[46:49]
	s_nop 2
	ds_read_b128 v[46:49], v142 offset:62592
	v_cvt_pk_bf16_f32 v10, v9, v10
	v_cvt_pk_bf16_f32 v11, v11, v12
	v_cvt_pk_bf16_f32 v12, v13, v14
	v_cvt_pk_bf16_f32 v13, v15, v52
	v_cvt_pk_bf16_f32 v2, v1, v2
	v_cvt_pk_bf16_f32 v3, v3, v4
	v_cvt_pk_bf16_f32 v4, v5, v6
	v_cvt_pk_bf16_f32 v5, v7, v16
	ds_read_b128 v[14:17], v142 offset:37312
	s_waitcnt lgkmcnt(1)
	v_mfma_f32_16x16x32_bf16 v[18:21], v[46:49], v[18:21], v[26:29]
	v_or_b32_e32 v6, 0x60, v132
	v_ashrrev_i32_e32 v7, 31, v6
	v_lshlrev_b64 v[6:7], 12, v[6:7]
	s_waitcnt lgkmcnt(0)
	v_mfma_f32_16x16x32_bf16 v[26:29], v[14:17], v[10:13], v[54:57]
	v_lshl_add_u64 v[6:7], v[134:135], 0, v[6:7]
	s_nop 6
	v_mfma_f32_16x16x32_bf16 v[14:17], v[14:17], v[2:5], v[22:25]
	s_nop 1
	ds_read_b128 v[22:25], v142 offset:45760
	v_mfma_f32_16x16x32_bf16 v[42:45], v[78:81], v[42:45], v[70:73]
	v_mfma_f32_16x16x32_bf16 v[34:37], v[46:49], v[34:37], v[42:45]
	s_waitcnt lgkmcnt(0)
	v_mfma_f32_16x16x32_bf16 v[42:45], v[22:25], v[10:13], v[58:61]
	v_mfma_f32_16x16x32_bf16 v[22:25], v[22:25], v[2:5], v[30:33]
	s_nop 2
	ds_read_b128 v[30:33], v142 offset:54208
	s_waitcnt lgkmcnt(0)
	v_mfma_f32_16x16x32_bf16 v[46:49], v[30:33], v[10:13], v[62:65]
	v_mfma_f32_16x16x32_bf16 v[30:33], v[30:33], v[2:5], v[38:41]
	s_nop 2
	ds_read_b128 v[38:41], v142 offset:62656
	s_waitcnt lgkmcnt(0)
	v_mfma_f32_16x16x32_bf16 v[2:5], v[38:41], v[2:5], v[18:21]
	v_mfma_f32_16x16x32_bf16 v[10:13], v[38:41], v[10:13], v[34:37]
	v_mul_f32_e32 v26, v8, v26
	v_mul_f32_e32 v27, v8, v27
	v_mul_f32_e32 v28, v8, v28
	v_mul_f32_e32 v29, v8, v29
	v_mul_f32_e32 v42, v8, v42
	v_mul_f32_e32 v43, v8, v43
	v_mul_f32_e32 v44, v8, v44
	v_mul_f32_e32 v45, v8, v45
	v_mul_f32_e32 v46, v8, v46
	v_mul_f32_e32 v47, v8, v47
	v_mul_f32_e32 v48, v8, v48
	v_mul_f32_e32 v49, v8, v49
	v_mul_f32_e32 v10, v8, v10
	v_mul_f32_e32 v11, v8, v11
	v_mul_f32_e32 v12, v8, v12
	v_mul_f32_e32 v13, v8, v13
	v_cvt_pk_bf16_f32 v26, v26, v27
	v_cvt_pk_bf16_f32 v27, v28, v29
	v_cvt_pk_bf16_f32 v28, v42, v43
	v_cvt_pk_bf16_f32 v29, v44, v45
	v_cvt_pk_bf16_f32 v46, v46, v47
	v_cvt_pk_bf16_f32 v47, v48, v49
	v_cvt_pk_bf16_f32 v48, v10, v11
	v_cvt_pk_bf16_f32 v49, v12, v13
	s_nop 1
	v_permlane16_swap_b32_e32 v26, v28
	v_permlane16_swap_b32_e32 v27, v29
	v_permlane16_swap_b32_e32 v46, v48
	v_permlane16_swap_b32_e32 v47, v49
	global_store_dwordx4 v[6:7], v[26:29], off
	global_store_dwordx4 v[6:7], v[46:49], off offset:64
	v_or_b32_e32 v6, 0x70, v132
	v_ashrrev_i32_e32 v7, 31, v6
	v_lshlrev_b64 v[6:7], 12, v[6:7]
	v_lshl_add_u64 v[6:7], v[134:135], 0, v[6:7]
	v_mul_f32_e32 v14, v0, v14
	v_mul_f32_e32 v15, v0, v15
	v_mul_f32_e32 v16, v0, v16
	v_mul_f32_e32 v17, v0, v17
	v_mul_f32_e32 v22, v0, v22
	v_mul_f32_e32 v23, v0, v23
	v_mul_f32_e32 v24, v0, v24
	v_mul_f32_e32 v25, v0, v25
	v_mul_f32_e32 v30, v0, v30
	v_mul_f32_e32 v31, v0, v31
	v_mul_f32_e32 v32, v0, v32
	v_mul_f32_e32 v33, v0, v33
	v_mul_f32_e32 v2, v0, v2
	v_mul_f32_e32 v3, v0, v3
	v_mul_f32_e32 v4, v0, v4
	v_mul_f32_e32 v5, v0, v5
	v_cvt_pk_bf16_f32 v14, v14, v15
	v_cvt_pk_bf16_f32 v15, v16, v17
	v_cvt_pk_bf16_f32 v16, v22, v23
	v_cvt_pk_bf16_f32 v17, v24, v25
	v_cvt_pk_bf16_f32 v30, v30, v31
	v_cvt_pk_bf16_f32 v31, v32, v33
	v_cvt_pk_bf16_f32 v32, v2, v3
	v_cvt_pk_bf16_f32 v33, v4, v5
	s_nop 1
	v_permlane16_swap_b32_e32 v14, v16
	v_permlane16_swap_b32_e32 v15, v17
	v_permlane16_swap_b32_e32 v30, v32
	v_permlane16_swap_b32_e32 v31, v33
	global_store_dwordx4 v[6:7], v[14:17], off
	global_store_dwordx4 v[6:7], v[30:33], off offset:64
	s_barrier
	s_cbranch_vccnz .LBB0_151
